# cache-policy bits on the LDS-DMA loads: sc1 (agent scope, no per-CU L1 allocation) on every global_load_lds in gemm_in and gemm_out
# baseline (speedup 1.0000x reference)
.LBB0_316:
	s_bfe_u32 s0, s9, 0xd0003
	s_mul_i32 s4, s0, 0x2493
	s_lshr_b32 s4, s4, 16
	s_mul_i32 s7, s4, 37
	s_lshr_b32 s8, s7, 8
	s_sub_i32 s8, s4, s8
	s_bfe_u32 s8, s8, 0x70001
	s_bfe_u32 s7, s7, 0x80008
	s_add_i32 s8, s8, s7
	s_bfe_u32 s7, s8, 0x60002
	s_mul_i32 s5, s4, 56
	s_mul_i32 s7, s7, 7
	s_sub_i32 s5, s9, s5
	s_sub_i32 s4, s4, s7
	s_and_b32 s6, s5, 0xffff
	s_mulk_i32 s0, 0xa73
	s_mul_i32 s4, s4, 7
	s_and_b32 s4, s4, 0xff
	s_bfe_u32 s16, s5, 0xd0003
	s_lshr_b32 s0, s0, 6
	s_lshl_b32 s8, s6, 8
	s_add_i32 s16, s16, s4
	s_and_b32 s0, s0, 0xf800
	s_and_b32 s4, s8, 0x700
	s_or_b32 s0, s4, s0
	s_lshl_b32 s4, s16, 19
	s_add_u32 s4, s12, s4
	s_addc_u32 s5, s13, 0
	s_lshl_b32 s6, s0, 12
	v_readlane_b32 s10, v254, 12
	v_readlane_b32 s11, v254, 13
	s_add_u32 s6, s10, s6
	s_addc_u32 s7, s11, 0
	v_lshrrev_b32_e32 v134, 6, v171
	v_and_b32_e32 v135, 63, v171
	v_readfirstlane_b32 s11, v134
	v_lshrrev_b32_e32 v175, 4, v135
	v_and_b32_e32 v128, 7, v135
	v_lshrrev_b32_e32 v129, 3, v135
	s_and_b32 s18, s11, 1
	s_lshl_b32 s18, s18, 2
	v_or_b32_e32 v176, s18, v175
	v_xor_b32_e32 v128, v128, v176
	v_lshlrev_b32_e32 v128, 4, v128
	v_lshl_or_b32 v128, v129, 12, v128
	s_lshl_b32 s18, s11, 15
	v_add_u32_e32 v128, s18, v128
	v_add_u32_e32 v129, 0x20000, v128
	v_add_u32_e32 v130, 0x40000, v128
	v_add_u32_e32 v131, 0x60000, v128
	v_add_u32_e32 v132, 0x80000, v128
	v_add_u32_e32 v133, 0xa0000, v128
	v_and_b32_e32 v134, 15, v135
	v_bfe_u32 v176, v134, 1, 3
	v_xor_b32_e32 v176, v176, v175
	v_lshlrev_b32_e32 v176, 4, v176
	v_lshl_or_b32 v176, v134, 7, v176
	s_and_b32 s18, s11, 1
	s_lshl_b32 s18, s18, 13
	v_add_u32_e32 v175, s18, v176
	s_lshr_b32 s19, s11, 1
	s_lshl_b32 s19, s19, 13
	v_add_u32_e32 v176, s19, v176
	v_xor_b32_e32 v177, 64, v175
	v_xor_b32_e32 v178, 64, v176
	s_lshl_b32 s11, s11, 10
	s_barrier
	s_add_u32 s18, s6, 0x40000
	s_addc_u32 s19, s7, 0
	s_add_u32 m0, s11, 0x4000
	s_nop 0
	global_load_lds_dwordx4 v128, s[6:7] sc1
	s_add_u32 m0, s11, 0x5000
	s_nop 0
	global_load_lds_dwordx4 v129, s[6:7] sc1
	s_add_u32 m0, s11, 0x6000
	s_nop 0
	global_load_lds_dwordx4 v132, s[6:7] sc1
	s_add_u32 m0, s11, 0x7000
	s_nop 0
	global_load_lds_dwordx4 v133, s[6:7] sc1
	s_add_u32 s6, s6, 128
	s_addc_u32 s7, s7, 0
	s_add_u32 m0, s11, 0x0
	s_nop 0
	global_load_lds_dwordx4 v128, s[4:5] sc1
	s_add_u32 m0, s11, 0x1000
	s_nop 0
	global_load_lds_dwordx4 v129, s[4:5] sc1
	s_add_u32 m0, s11, 0x2000
	s_nop 0
	global_load_lds_dwordx4 v130, s[4:5] sc1
	s_add_u32 m0, s11, 0x3000
	s_nop 0
	global_load_lds_dwordx4 v131, s[4:5] sc1
	s_add_u32 s4, s4, 128
	s_addc_u32 s5, s5, 0
	s_add_u32 m0, s11, 0x8000
	s_nop 0
	global_load_lds_dwordx4 v128, s[18:19] sc1
	s_add_u32 m0, s11, 0x9000
	s_nop 0
	global_load_lds_dwordx4 v129, s[18:19] sc1
	s_add_u32 m0, s11, 0xa000
	s_nop 0
	global_load_lds_dwordx4 v132, s[18:19] sc1
	s_add_u32 m0, s11, 0xb000
	s_nop 0
	global_load_lds_dwordx4 v133, s[18:19] sc1
	s_add_u32 s18, s18, 128
	s_addc_u32 s19, s19, 0
	v_mov_b32_e32 v0, 0
	v_mov_b32_e32 v1, v0
	v_mov_b32_e32 v2, v0
	v_mov_b32_e32 v3, v0
	v_mov_b32_e32 v4, v0
	v_mov_b32_e32 v5, v0
	v_mov_b32_e32 v6, v0
	v_mov_b32_e32 v7, v0
	v_mov_b32_e32 v8, v0
	v_mov_b32_e32 v9, v0
	v_mov_b32_e32 v10, v0
	v_mov_b32_e32 v11, v0
	v_mov_b32_e32 v12, v0
	v_mov_b32_e32 v13, v0
	v_mov_b32_e32 v14, v0
	v_mov_b32_e32 v15, v0
	v_mov_b32_e32 v16, v0
	v_mov_b32_e32 v17, v0
	v_mov_b32_e32 v18, v0
	v_mov_b32_e32 v19, v0
	v_mov_b32_e32 v20, v0
	v_mov_b32_e32 v21, v0
	v_mov_b32_e32 v22, v0
	v_mov_b32_e32 v23, v0
	v_mov_b32_e32 v24, v0
	v_mov_b32_e32 v25, v0
	v_mov_b32_e32 v26, v0
	v_mov_b32_e32 v27, v0
	v_mov_b32_e32 v28, v0
	v_mov_b32_e32 v29, v0
	v_mov_b32_e32 v30, v0
	v_mov_b32_e32 v31, v0
	v_mov_b32_e32 v32, v0
	v_mov_b32_e32 v33, v0
	v_mov_b32_e32 v34, v0
	v_mov_b32_e32 v35, v0
	v_mov_b32_e32 v36, v0
	v_mov_b32_e32 v37, v0
	v_mov_b32_e32 v38, v0
	v_mov_b32_e32 v39, v0
	v_mov_b32_e32 v40, v0
	v_mov_b32_e32 v41, v0
	v_mov_b32_e32 v42, v0
	v_mov_b32_e32 v43, v0
	v_mov_b32_e32 v44, v0
	v_mov_b32_e32 v45, v0
	v_mov_b32_e32 v46, v0
	v_mov_b32_e32 v47, v0
	v_mov_b32_e32 v48, v0
	v_mov_b32_e32 v49, v0
	v_mov_b32_e32 v50, v0
	v_mov_b32_e32 v51, v0
	v_mov_b32_e32 v52, v0
	v_mov_b32_e32 v53, v0
	v_mov_b32_e32 v54, v0
	v_mov_b32_e32 v55, v0
	v_mov_b32_e32 v56, v0
	v_mov_b32_e32 v57, v0
	v_mov_b32_e32 v58, v0
	v_mov_b32_e32 v59, v0
	v_mov_b32_e32 v60, v0
	v_mov_b32_e32 v61, v0
	v_mov_b32_e32 v62, v0
	v_mov_b32_e32 v63, v0
	v_mov_b32_e32 v64, v0
	v_mov_b32_e32 v65, v0
	v_mov_b32_e32 v66, v0
	v_mov_b32_e32 v67, v0
	v_mov_b32_e32 v68, v0
	v_mov_b32_e32 v69, v0
	v_mov_b32_e32 v70, v0
	v_mov_b32_e32 v71, v0
	v_mov_b32_e32 v72, v0
	v_mov_b32_e32 v73, v0
	v_mov_b32_e32 v74, v0
	v_mov_b32_e32 v75, v0
	v_mov_b32_e32 v76, v0
	v_mov_b32_e32 v77, v0
	v_mov_b32_e32 v78, v0
	v_mov_b32_e32 v79, v0
	v_mov_b32_e32 v80, v0
	v_mov_b32_e32 v81, v0
	v_mov_b32_e32 v82, v0
	v_mov_b32_e32 v83, v0
	v_mov_b32_e32 v84, v0
	v_mov_b32_e32 v85, v0
	v_mov_b32_e32 v86, v0
	v_mov_b32_e32 v87, v0
	v_mov_b32_e32 v88, v0
	v_mov_b32_e32 v89, v0
	v_mov_b32_e32 v90, v0
	v_mov_b32_e32 v91, v0
	v_mov_b32_e32 v92, v0
	v_mov_b32_e32 v93, v0
	v_mov_b32_e32 v94, v0
	v_mov_b32_e32 v95, v0
	v_mov_b32_e32 v96, v0
	v_mov_b32_e32 v97, v0
	v_mov_b32_e32 v98, v0
	v_mov_b32_e32 v99, v0
	v_mov_b32_e32 v100, v0
	v_mov_b32_e32 v101, v0
	v_mov_b32_e32 v102, v0
	v_mov_b32_e32 v103, v0
	v_mov_b32_e32 v104, v0
	v_mov_b32_e32 v105, v0
	v_mov_b32_e32 v106, v0
	v_mov_b32_e32 v107, v0
	v_mov_b32_e32 v108, v0
	v_mov_b32_e32 v109, v0
	v_mov_b32_e32 v110, v0
	v_mov_b32_e32 v111, v0
	v_mov_b32_e32 v112, v0
	v_mov_b32_e32 v113, v0
	v_mov_b32_e32 v114, v0
	v_mov_b32_e32 v115, v0
	v_mov_b32_e32 v116, v0
	v_mov_b32_e32 v117, v0
	v_mov_b32_e32 v118, v0
	v_mov_b32_e32 v119, v0
	v_mov_b32_e32 v120, v0
	v_mov_b32_e32 v121, v0
	v_mov_b32_e32 v122, v0
	v_mov_b32_e32 v123, v0
	v_mov_b32_e32 v124, v0
	v_mov_b32_e32 v125, v0
	v_mov_b32_e32 v126, v0
	v_mov_b32_e32 v127, v0
	s_mov_b32 s10, 0
.Lgin_loop:
	s_waitcnt vmcnt(4)
	s_barrier
	ds_read_b128 v[230:233], v175 offset:0
	ds_read_b128 v[234:237], v175 offset:2048
	ds_read_b128 v[238:241], v175 offset:4096
	ds_read_b128 v[242:245], v175 offset:6144
	ds_read_b128 v[136:139], v177 offset:0
	ds_read_b128 v[140:143], v177 offset:2048
	ds_read_b128 v[144:147], v177 offset:4096
	ds_read_b128 v[148:151], v177 offset:6144
	ds_read_b128 v[182:185], v176 offset:16384
	ds_read_b128 v[186:189], v176 offset:18432
	ds_read_b128 v[190:193], v176 offset:20480
	ds_read_b128 v[194:197], v176 offset:22528
	s_add_u32 m0, s11, 0xc000
	s_waitcnt lgkmcnt(3)
	v_mfma_f32_16x16x32_f16 v[124:127], v[230:233], v[182:185], v[124:127]
	v_mfma_f32_16x16x32_f16 v[92:95], v[234:237], v[182:185], v[92:95]
	v_mfma_f32_16x16x32_f16 v[60:63], v[238:241], v[182:185], v[60:63]
	v_mfma_f32_16x16x32_f16 v[28:31], v[242:245], v[182:185], v[28:31]
	global_load_lds_dwordx4 v128, s[6:7] sc1
	s_barrier
	ds_read_b128 v[198:201], v178 offset:16384
	ds_read_b128 v[202:205], v178 offset:18432
	ds_read_b128 v[222:225], v178 offset:20480
	ds_read_b128 v[226:229], v178 offset:22528
	s_add_u32 m0, s11, 0xd000
	s_waitcnt lgkmcnt(6)
	v_mfma_f32_16x16x32_f16 v[120:123], v[230:233], v[186:189], v[120:123]
	v_mfma_f32_16x16x32_f16 v[88:91], v[234:237], v[186:189], v[88:91]
	v_mfma_f32_16x16x32_f16 v[56:59], v[238:241], v[186:189], v[56:59]
	v_mfma_f32_16x16x32_f16 v[24:27], v[242:245], v[186:189], v[24:27]
	global_load_lds_dwordx4 v129, s[6:7] sc1
	s_add_u32 m0, s11, 0xe000
	s_waitcnt lgkmcnt(5)
	v_mfma_f32_16x16x32_f16 v[116:119], v[230:233], v[190:193], v[116:119]
	v_mfma_f32_16x16x32_f16 v[84:87], v[234:237], v[190:193], v[84:87]
	v_mfma_f32_16x16x32_f16 v[52:55], v[238:241], v[190:193], v[52:55]
	v_mfma_f32_16x16x32_f16 v[20:23], v[242:245], v[190:193], v[20:23]
	global_load_lds_dwordx4 v132, s[6:7] sc1
	s_add_u32 m0, s11, 0xf000
	s_waitcnt lgkmcnt(4)
	v_mfma_f32_16x16x32_f16 v[112:115], v[230:233], v[194:197], v[112:115]
	v_mfma_f32_16x16x32_f16 v[80:83], v[234:237], v[194:197], v[80:83]
	v_mfma_f32_16x16x32_f16 v[48:51], v[238:241], v[194:197], v[48:51]
	v_mfma_f32_16x16x32_f16 v[16:19], v[242:245], v[194:197], v[16:19]
	global_load_lds_dwordx4 v133, s[6:7] sc1
	s_add_u32 m0, s11, 0x0
	s_waitcnt lgkmcnt(3)
	v_mfma_f32_16x16x32_f16 v[124:127], v[136:139], v[198:201], v[124:127]
	v_mfma_f32_16x16x32_f16 v[92:95], v[140:143], v[198:201], v[92:95]
	v_mfma_f32_16x16x32_f16 v[60:63], v[144:147], v[198:201], v[60:63]
	v_mfma_f32_16x16x32_f16 v[28:31], v[148:151], v[198:201], v[28:31]
	global_load_lds_dwordx4 v128, s[4:5] sc1
	s_add_u32 m0, s11, 0x1000
	s_waitcnt lgkmcnt(2)
	v_mfma_f32_16x16x32_f16 v[120:123], v[136:139], v[202:205], v[120:123]
	v_mfma_f32_16x16x32_f16 v[88:91], v[140:143], v[202:205], v[88:91]
	v_mfma_f32_16x16x32_f16 v[56:59], v[144:147], v[202:205], v[56:59]
	v_mfma_f32_16x16x32_f16 v[24:27], v[148:151], v[202:205], v[24:27]
	global_load_lds_dwordx4 v129, s[4:5] sc1
	s_add_u32 m0, s11, 0x2000
	s_waitcnt lgkmcnt(1)
	v_mfma_f32_16x16x32_f16 v[116:119], v[136:139], v[222:225], v[116:119]
	v_mfma_f32_16x16x32_f16 v[84:87], v[140:143], v[222:225], v[84:87]
	v_mfma_f32_16x16x32_f16 v[52:55], v[144:147], v[222:225], v[52:55]
	v_mfma_f32_16x16x32_f16 v[20:23], v[148:151], v[222:225], v[20:23]
	global_load_lds_dwordx4 v130, s[4:5] sc1
	s_add_u32 m0, s11, 0x3000
	s_waitcnt lgkmcnt(0)
	v_mfma_f32_16x16x32_f16 v[112:115], v[136:139], v[226:229], v[112:115]
	v_mfma_f32_16x16x32_f16 v[80:83], v[140:143], v[226:229], v[80:83]
	v_mfma_f32_16x16x32_f16 v[48:51], v[144:147], v[226:229], v[48:51]
	v_mfma_f32_16x16x32_f16 v[16:19], v[148:151], v[226:229], v[16:19]
	global_load_lds_dwordx4 v131, s[4:5] sc1
	s_add_u32 s6, s6, 128
	s_addc_u32 s7, s7, 0
	s_add_u32 s4, s4, 128
	s_addc_u32 s5, s5, 0
	s_waitcnt vmcnt(8)
	s_barrier
	ds_read_b128 v[182:185], v176 offset:32768
	ds_read_b128 v[186:189], v176 offset:34816
	ds_read_b128 v[190:193], v176 offset:36864
	ds_read_b128 v[194:197], v176 offset:38912
	ds_read_b128 v[198:201], v178 offset:32768
	ds_read_b128 v[202:205], v178 offset:34816
	ds_read_b128 v[222:225], v178 offset:36864
	ds_read_b128 v[226:229], v178 offset:38912
	s_add_u32 m0, s11, 0x4000
	s_waitcnt lgkmcnt(7)
	v_mfma_f32_16x16x32_f16 v[108:111], v[230:233], v[182:185], v[108:111]
	v_mfma_f32_16x16x32_f16 v[76:79], v[234:237], v[182:185], v[76:79]
	v_mfma_f32_16x16x32_f16 v[44:47], v[238:241], v[182:185], v[44:47]
	v_mfma_f32_16x16x32_f16 v[12:15], v[242:245], v[182:185], v[12:15]
	global_load_lds_dwordx4 v128, s[18:19] sc1
	s_add_u32 m0, s11, 0x5000
	s_waitcnt lgkmcnt(6)
	v_mfma_f32_16x16x32_f16 v[104:107], v[230:233], v[186:189], v[104:107]
	v_mfma_f32_16x16x32_f16 v[72:75], v[234:237], v[186:189], v[72:75]
	v_mfma_f32_16x16x32_f16 v[40:43], v[238:241], v[186:189], v[40:43]
	v_mfma_f32_16x16x32_f16 v[8:11], v[242:245], v[186:189], v[8:11]
	global_load_lds_dwordx4 v129, s[18:19] sc1
	s_add_u32 m0, s11, 0x6000
	s_waitcnt lgkmcnt(5)
	v_mfma_f32_16x16x32_f16 v[100:103], v[230:233], v[190:193], v[100:103]
	v_mfma_f32_16x16x32_f16 v[68:71], v[234:237], v[190:193], v[68:71]
	v_mfma_f32_16x16x32_f16 v[36:39], v[238:241], v[190:193], v[36:39]
	v_mfma_f32_16x16x32_f16 v[4:7], v[242:245], v[190:193], v[4:7]
	global_load_lds_dwordx4 v132, s[18:19] sc1
	s_add_u32 m0, s11, 0x7000
	s_waitcnt lgkmcnt(4)
	v_mfma_f32_16x16x32_f16 v[96:99], v[230:233], v[194:197], v[96:99]
	v_mfma_f32_16x16x32_f16 v[64:67], v[234:237], v[194:197], v[64:67]
	v_mfma_f32_16x16x32_f16 v[32:35], v[238:241], v[194:197], v[32:35]
	v_mfma_f32_16x16x32_f16 v[0:3], v[242:245], v[194:197], v[0:3]
	global_load_lds_dwordx4 v133, s[18:19] sc1
	s_waitcnt lgkmcnt(3)
	v_mfma_f32_16x16x32_f16 v[108:111], v[136:139], v[198:201], v[108:111]
	v_mfma_f32_16x16x32_f16 v[76:79], v[140:143], v[198:201], v[76:79]
	v_mfma_f32_16x16x32_f16 v[44:47], v[144:147], v[198:201], v[44:47]
	v_mfma_f32_16x16x32_f16 v[12:15], v[148:151], v[198:201], v[12:15]
	s_waitcnt lgkmcnt(2)
	v_mfma_f32_16x16x32_f16 v[104:107], v[136:139], v[202:205], v[104:107]
	v_mfma_f32_16x16x32_f16 v[72:75], v[140:143], v[202:205], v[72:75]
	v_mfma_f32_16x16x32_f16 v[40:43], v[144:147], v[202:205], v[40:43]
	v_mfma_f32_16x16x32_f16 v[8:11], v[148:151], v[202:205], v[8:11]
	s_waitcnt lgkmcnt(1)
	v_mfma_f32_16x16x32_f16 v[100:103], v[136:139], v[222:225], v[100:103]
	v_mfma_f32_16x16x32_f16 v[68:71], v[140:143], v[222:225], v[68:71]
	v_mfma_f32_16x16x32_f16 v[36:39], v[144:147], v[222:225], v[36:39]
	v_mfma_f32_16x16x32_f16 v[4:7], v[148:151], v[222:225], v[4:7]
	s_waitcnt lgkmcnt(0)
	v_mfma_f32_16x16x32_f16 v[96:99], v[136:139], v[226:229], v[96:99]
	v_mfma_f32_16x16x32_f16 v[64:67], v[140:143], v[226:229], v[64:67]
	v_mfma_f32_16x16x32_f16 v[32:35], v[144:147], v[226:229], v[32:35]
	v_mfma_f32_16x16x32_f16 v[0:3], v[148:151], v[226:229], v[0:3]
	s_add_u32 s18, s18, 128
	s_addc_u32 s19, s19, 0
	s_waitcnt vmcnt(4)
	s_barrier
	ds_read_b128 v[230:233], v175 offset:0
	ds_read_b128 v[234:237], v175 offset:2048
	ds_read_b128 v[238:241], v175 offset:4096
	ds_read_b128 v[242:245], v175 offset:6144
	ds_read_b128 v[136:139], v177 offset:0
	ds_read_b128 v[140:143], v177 offset:2048
	ds_read_b128 v[144:147], v177 offset:4096
	ds_read_b128 v[148:151], v177 offset:6144
	ds_read_b128 v[182:185], v176 offset:49152
	ds_read_b128 v[186:189], v176 offset:51200
	ds_read_b128 v[190:193], v176 offset:53248
	ds_read_b128 v[194:197], v176 offset:55296
	s_add_u32 m0, s11, 0x8000
	s_waitcnt lgkmcnt(3)
	v_mfma_f32_16x16x32_f16 v[124:127], v[230:233], v[182:185], v[124:127]
	v_mfma_f32_16x16x32_f16 v[92:95], v[234:237], v[182:185], v[92:95]
	v_mfma_f32_16x16x32_f16 v[60:63], v[238:241], v[182:185], v[60:63]
	v_mfma_f32_16x16x32_f16 v[28:31], v[242:245], v[182:185], v[28:31]
	global_load_lds_dwordx4 v128, s[6:7] sc1
	s_barrier
	ds_read_b128 v[198:201], v178 offset:49152
	ds_read_b128 v[202:205], v178 offset:51200
	ds_read_b128 v[222:225], v178 offset:53248
	ds_read_b128 v[226:229], v178 offset:55296
	s_add_u32 m0, s11, 0x9000
	s_waitcnt lgkmcnt(6)
	v_mfma_f32_16x16x32_f16 v[120:123], v[230:233], v[186:189], v[120:123]
	v_mfma_f32_16x16x32_f16 v[88:91], v[234:237], v[186:189], v[88:91]
	v_mfma_f32_16x16x32_f16 v[56:59], v[238:241], v[186:189], v[56:59]
	v_mfma_f32_16x16x32_f16 v[24:27], v[242:245], v[186:189], v[24:27]
	global_load_lds_dwordx4 v129, s[6:7] sc1
	s_add_u32 m0, s11, 0xa000
	s_waitcnt lgkmcnt(5)
	v_mfma_f32_16x16x32_f16 v[116:119], v[230:233], v[190:193], v[116:119]
	v_mfma_f32_16x16x32_f16 v[84:87], v[234:237], v[190:193], v[84:87]
	v_mfma_f32_16x16x32_f16 v[52:55], v[238:241], v[190:193], v[52:55]
	v_mfma_f32_16x16x32_f16 v[20:23], v[242:245], v[190:193], v[20:23]
	global_load_lds_dwordx4 v132, s[6:7] sc1
	s_add_u32 m0, s11, 0xb000
	s_waitcnt lgkmcnt(4)
	v_mfma_f32_16x16x32_f16 v[112:115], v[230:233], v[194:197], v[112:115]
	v_mfma_f32_16x16x32_f16 v[80:83], v[234:237], v[194:197], v[80:83]
	v_mfma_f32_16x16x32_f16 v[48:51], v[238:241], v[194:197], v[48:51]
	v_mfma_f32_16x16x32_f16 v[16:19], v[242:245], v[194:197], v[16:19]
	global_load_lds_dwordx4 v133, s[6:7] sc1
	s_add_u32 m0, s11, 0x0
	s_waitcnt lgkmcnt(3)
	v_mfma_f32_16x16x32_f16 v[124:127], v[136:139], v[198:201], v[124:127]
	v_mfma_f32_16x16x32_f16 v[92:95], v[140:143], v[198:201], v[92:95]
	v_mfma_f32_16x16x32_f16 v[60:63], v[144:147], v[198:201], v[60:63]
	v_mfma_f32_16x16x32_f16 v[28:31], v[148:151], v[198:201], v[28:31]
	global_load_lds_dwordx4 v128, s[4:5] sc1
	s_add_u32 m0, s11, 0x1000
	s_waitcnt lgkmcnt(2)
	v_mfma_f32_16x16x32_f16 v[120:123], v[136:139], v[202:205], v[120:123]
	v_mfma_f32_16x16x32_f16 v[88:91], v[140:143], v[202:205], v[88:91]
	v_mfma_f32_16x16x32_f16 v[56:59], v[144:147], v[202:205], v[56:59]
	v_mfma_f32_16x16x32_f16 v[24:27], v[148:151], v[202:205], v[24:27]
	global_load_lds_dwordx4 v129, s[4:5] sc1
	s_add_u32 m0, s11, 0x2000
	s_waitcnt lgkmcnt(1)
	v_mfma_f32_16x16x32_f16 v[116:119], v[136:139], v[222:225], v[116:119]
	v_mfma_f32_16x16x32_f16 v[84:87], v[140:143], v[222:225], v[84:87]
	v_mfma_f32_16x16x32_f16 v[52:55], v[144:147], v[222:225], v[52:55]
	v_mfma_f32_16x16x32_f16 v[20:23], v[148:151], v[222:225], v[20:23]
	global_load_lds_dwordx4 v130, s[4:5] sc1
	s_add_u32 m0, s11, 0x3000
	s_waitcnt lgkmcnt(0)
	v_mfma_f32_16x16x32_f16 v[112:115], v[136:139], v[226:229], v[112:115]
	v_mfma_f32_16x16x32_f16 v[80:83], v[140:143], v[226:229], v[80:83]
	v_mfma_f32_16x16x32_f16 v[48:51], v[144:147], v[226:229], v[48:51]
	v_mfma_f32_16x16x32_f16 v[16:19], v[148:151], v[226:229], v[16:19]
	global_load_lds_dwordx4 v131, s[4:5] sc1
	s_add_u32 s6, s6, 128
	s_addc_u32 s7, s7, 0
	s_add_u32 s4, s4, 128
	s_addc_u32 s5, s5, 0
	s_waitcnt vmcnt(8)
	s_barrier
	ds_read_b128 v[182:185], v176 offset:16384
	ds_read_b128 v[186:189], v176 offset:18432
	ds_read_b128 v[190:193], v176 offset:20480
	ds_read_b128 v[194:197], v176 offset:22528
	ds_read_b128 v[198:201], v178 offset:16384
	ds_read_b128 v[202:205], v178 offset:18432
	ds_read_b128 v[222:225], v178 offset:20480
	ds_read_b128 v[226:229], v178 offset:22528
	s_add_u32 m0, s11, 0xc000
	s_waitcnt lgkmcnt(7)
	v_mfma_f32_16x16x32_f16 v[108:111], v[230:233], v[182:185], v[108:111]
	v_mfma_f32_16x16x32_f16 v[76:79], v[234:237], v[182:185], v[76:79]
	v_mfma_f32_16x16x32_f16 v[44:47], v[238:241], v[182:185], v[44:47]
	v_mfma_f32_16x16x32_f16 v[12:15], v[242:245], v[182:185], v[12:15]
	global_load_lds_dwordx4 v128, s[18:19] sc1
	s_add_u32 m0, s11, 0xd000
	s_waitcnt lgkmcnt(6)
	v_mfma_f32_16x16x32_f16 v[104:107], v[230:233], v[186:189], v[104:107]
	v_mfma_f32_16x16x32_f16 v[72:75], v[234:237], v[186:189], v[72:75]
	v_mfma_f32_16x16x32_f16 v[40:43], v[238:241], v[186:189], v[40:43]
	v_mfma_f32_16x16x32_f16 v[8:11], v[242:245], v[186:189], v[8:11]
	global_load_lds_dwordx4 v129, s[18:19] sc1
	s_add_u32 m0, s11, 0xe000
	s_waitcnt lgkmcnt(5)
	v_mfma_f32_16x16x32_f16 v[100:103], v[230:233], v[190:193], v[100:103]
	v_mfma_f32_16x16x32_f16 v[68:71], v[234:237], v[190:193], v[68:71]
	v_mfma_f32_16x16x32_f16 v[36:39], v[238:241], v[190:193], v[36:39]
	v_mfma_f32_16x16x32_f16 v[4:7], v[242:245], v[190:193], v[4:7]
	global_load_lds_dwordx4 v132, s[18:19] sc1
	s_add_u32 m0, s11, 0xf000
	s_waitcnt lgkmcnt(4)
	v_mfma_f32_16x16x32_f16 v[96:99], v[230:233], v[194:197], v[96:99]
	v_mfma_f32_16x16x32_f16 v[64:67], v[234:237], v[194:197], v[64:67]
	v_mfma_f32_16x16x32_f16 v[32:35], v[238:241], v[194:197], v[32:35]
	v_mfma_f32_16x16x32_f16 v[0:3], v[242:245], v[194:197], v[0:3]
	global_load_lds_dwordx4 v133, s[18:19] sc1
	s_waitcnt lgkmcnt(3)
	v_mfma_f32_16x16x32_f16 v[108:111], v[136:139], v[198:201], v[108:111]
	v_mfma_f32_16x16x32_f16 v[76:79], v[140:143], v[198:201], v[76:79]
	v_mfma_f32_16x16x32_f16 v[44:47], v[144:147], v[198:201], v[44:47]
	v_mfma_f32_16x16x32_f16 v[12:15], v[148:151], v[198:201], v[12:15]
	s_waitcnt lgkmcnt(2)
	v_mfma_f32_16x16x32_f16 v[104:107], v[136:139], v[202:205], v[104:107]
	v_mfma_f32_16x16x32_f16 v[72:75], v[140:143], v[202:205], v[72:75]
	v_mfma_f32_16x16x32_f16 v[40:43], v[144:147], v[202:205], v[40:43]
	v_mfma_f32_16x16x32_f16 v[8:11], v[148:151], v[202:205], v[8:11]
	s_waitcnt lgkmcnt(1)
	v_mfma_f32_16x16x32_f16 v[100:103], v[136:139], v[222:225], v[100:103]
	v_mfma_f32_16x16x32_f16 v[68:71], v[140:143], v[222:225], v[68:71]
	v_mfma_f32_16x16x32_f16 v[36:39], v[144:147], v[222:225], v[36:39]
	v_mfma_f32_16x16x32_f16 v[4:7], v[148:151], v[222:225], v[4:7]
	s_waitcnt lgkmcnt(0)
	v_mfma_f32_16x16x32_f16 v[96:99], v[136:139], v[226:229], v[96:99]
	v_mfma_f32_16x16x32_f16 v[64:67], v[140:143], v[226:229], v[64:67]
	v_mfma_f32_16x16x32_f16 v[32:35], v[144:147], v[226:229], v[32:35]
	v_mfma_f32_16x16x32_f16 v[0:3], v[148:151], v[226:229], v[0:3]
	s_add_u32 s18, s18, 128
	s_addc_u32 s19, s19, 0
	s_waitcnt vmcnt(4)
	s_barrier
	ds_read_b128 v[230:233], v175 offset:0
	ds_read_b128 v[234:237], v175 offset:2048
	ds_read_b128 v[238:241], v175 offset:4096
	ds_read_b128 v[242:245], v175 offset:6144
	ds_read_b128 v[136:139], v177 offset:0
	ds_read_b128 v[140:143], v177 offset:2048
	ds_read_b128 v[144:147], v177 offset:4096
	ds_read_b128 v[148:151], v177 offset:6144
	ds_read_b128 v[182:185], v176 offset:32768
	ds_read_b128 v[186:189], v176 offset:34816
	ds_read_b128 v[190:193], v176 offset:36864
	ds_read_b128 v[194:197], v176 offset:38912
	s_add_u32 m0, s11, 0x4000
	s_waitcnt lgkmcnt(3)
	v_mfma_f32_16x16x32_f16 v[124:127], v[230:233], v[182:185], v[124:127]
	v_mfma_f32_16x16x32_f16 v[92:95], v[234:237], v[182:185], v[92:95]
	v_mfma_f32_16x16x32_f16 v[60:63], v[238:241], v[182:185], v[60:63]
	v_mfma_f32_16x16x32_f16 v[28:31], v[242:245], v[182:185], v[28:31]
	global_load_lds_dwordx4 v128, s[6:7] sc1
	s_barrier
	ds_read_b128 v[198:201], v178 offset:32768
	ds_read_b128 v[202:205], v178 offset:34816
	ds_read_b128 v[222:225], v178 offset:36864
	ds_read_b128 v[226:229], v178 offset:38912
	s_add_u32 m0, s11, 0x5000
	s_waitcnt lgkmcnt(6)
	v_mfma_f32_16x16x32_f16 v[120:123], v[230:233], v[186:189], v[120:123]
	v_mfma_f32_16x16x32_f16 v[88:91], v[234:237], v[186:189], v[88:91]
	v_mfma_f32_16x16x32_f16 v[56:59], v[238:241], v[186:189], v[56:59]
	v_mfma_f32_16x16x32_f16 v[24:27], v[242:245], v[186:189], v[24:27]
	global_load_lds_dwordx4 v129, s[6:7] sc1
	s_add_u32 m0, s11, 0x6000
	s_waitcnt lgkmcnt(5)
	v_mfma_f32_16x16x32_f16 v[116:119], v[230:233], v[190:193], v[116:119]
	v_mfma_f32_16x16x32_f16 v[84:87], v[234:237], v[190:193], v[84:87]
	v_mfma_f32_16x16x32_f16 v[52:55], v[238:241], v[190:193], v[52:55]
	v_mfma_f32_16x16x32_f16 v[20:23], v[242:245], v[190:193], v[20:23]
	global_load_lds_dwordx4 v132, s[6:7] sc1
	s_add_u32 m0, s11, 0x7000
	s_waitcnt lgkmcnt(4)
	v_mfma_f32_16x16x32_f16 v[112:115], v[230:233], v[194:197], v[112:115]
	v_mfma_f32_16x16x32_f16 v[80:83], v[234:237], v[194:197], v[80:83]
	v_mfma_f32_16x16x32_f16 v[48:51], v[238:241], v[194:197], v[48:51]
	v_mfma_f32_16x16x32_f16 v[16:19], v[242:245], v[194:197], v[16:19]
	global_load_lds_dwordx4 v133, s[6:7] sc1
	s_add_u32 m0, s11, 0x0
	s_waitcnt lgkmcnt(3)
	v_mfma_f32_16x16x32_f16 v[124:127], v[136:139], v[198:201], v[124:127]
	v_mfma_f32_16x16x32_f16 v[92:95], v[140:143], v[198:201], v[92:95]
	v_mfma_f32_16x16x32_f16 v[60:63], v[144:147], v[198:201], v[60:63]
	v_mfma_f32_16x16x32_f16 v[28:31], v[148:151], v[198:201], v[28:31]
	global_load_lds_dwordx4 v128, s[4:5] sc1
	s_add_u32 m0, s11, 0x1000
	s_waitcnt lgkmcnt(2)
	v_mfma_f32_16x16x32_f16 v[120:123], v[136:139], v[202:205], v[120:123]
	v_mfma_f32_16x16x32_f16 v[88:91], v[140:143], v[202:205], v[88:91]
	v_mfma_f32_16x16x32_f16 v[56:59], v[144:147], v[202:205], v[56:59]
	v_mfma_f32_16x16x32_f16 v[24:27], v[148:151], v[202:205], v[24:27]
	global_load_lds_dwordx4 v129, s[4:5] sc1
	s_add_u32 m0, s11, 0x2000
	s_waitcnt lgkmcnt(1)
	v_mfma_f32_16x16x32_f16 v[116:119], v[136:139], v[222:225], v[116:119]
	v_mfma_f32_16x16x32_f16 v[84:87], v[140:143], v[222:225], v[84:87]
	v_mfma_f32_16x16x32_f16 v[52:55], v[144:147], v[222:225], v[52:55]
	v_mfma_f32_16x16x32_f16 v[20:23], v[148:151], v[222:225], v[20:23]
	global_load_lds_dwordx4 v130, s[4:5] sc1
	s_add_u32 m0, s11, 0x3000
	s_waitcnt lgkmcnt(0)
	v_mfma_f32_16x16x32_f16 v[112:115], v[136:139], v[226:229], v[112:115]
	v_mfma_f32_16x16x32_f16 v[80:83], v[140:143], v[226:229], v[80:83]
	v_mfma_f32_16x16x32_f16 v[48:51], v[144:147], v[226:229], v[48:51]
	v_mfma_f32_16x16x32_f16 v[16:19], v[148:151], v[226:229], v[16:19]
	global_load_lds_dwordx4 v131, s[4:5] sc1
	s_add_u32 s6, s6, 128
	s_addc_u32 s7, s7, 0
	s_add_u32 s4, s4, 128
	s_addc_u32 s5, s5, 0
	s_waitcnt vmcnt(8)
	s_barrier
	ds_read_b128 v[182:185], v176 offset:49152
	ds_read_b128 v[186:189], v176 offset:51200
	ds_read_b128 v[190:193], v176 offset:53248
	ds_read_b128 v[194:197], v176 offset:55296
	ds_read_b128 v[198:201], v178 offset:49152
	ds_read_b128 v[202:205], v178 offset:51200
	ds_read_b128 v[222:225], v178 offset:53248
	ds_read_b128 v[226:229], v178 offset:55296
	s_add_u32 m0, s11, 0x8000
	s_waitcnt lgkmcnt(7)
	v_mfma_f32_16x16x32_f16 v[108:111], v[230:233], v[182:185], v[108:111]
	v_mfma_f32_16x16x32_f16 v[76:79], v[234:237], v[182:185], v[76:79]
	v_mfma_f32_16x16x32_f16 v[44:47], v[238:241], v[182:185], v[44:47]
	v_mfma_f32_16x16x32_f16 v[12:15], v[242:245], v[182:185], v[12:15]
	global_load_lds_dwordx4 v128, s[18:19] sc1
	s_add_u32 m0, s11, 0x9000
	s_waitcnt lgkmcnt(6)
	v_mfma_f32_16x16x32_f16 v[104:107], v[230:233], v[186:189], v[104:107]
	v_mfma_f32_16x16x32_f16 v[72:75], v[234:237], v[186:189], v[72:75]
	v_mfma_f32_16x16x32_f16 v[40:43], v[238:241], v[186:189], v[40:43]
	v_mfma_f32_16x16x32_f16 v[8:11], v[242:245], v[186:189], v[8:11]
	global_load_lds_dwordx4 v129, s[18:19] sc1
	s_add_u32 m0, s11, 0xa000
	s_waitcnt lgkmcnt(5)
	v_mfma_f32_16x16x32_f16 v[100:103], v[230:233], v[190:193], v[100:103]
	v_mfma_f32_16x16x32_f16 v[68:71], v[234:237], v[190:193], v[68:71]
	v_mfma_f32_16x16x32_f16 v[36:39], v[238:241], v[190:193], v[36:39]
	v_mfma_f32_16x16x32_f16 v[4:7], v[242:245], v[190:193], v[4:7]
	global_load_lds_dwordx4 v132, s[18:19] sc1
	s_add_u32 m0, s11, 0xb000
	s_waitcnt lgkmcnt(4)
	v_mfma_f32_16x16x32_f16 v[96:99], v[230:233], v[194:197], v[96:99]
	v_mfma_f32_16x16x32_f16 v[64:67], v[234:237], v[194:197], v[64:67]
	v_mfma_f32_16x16x32_f16 v[32:35], v[238:241], v[194:197], v[32:35]
	v_mfma_f32_16x16x32_f16 v[0:3], v[242:245], v[194:197], v[0:3]
	global_load_lds_dwordx4 v133, s[18:19] sc1
	s_waitcnt lgkmcnt(3)
	v_mfma_f32_16x16x32_f16 v[108:111], v[136:139], v[198:201], v[108:111]
	v_mfma_f32_16x16x32_f16 v[76:79], v[140:143], v[198:201], v[76:79]
	v_mfma_f32_16x16x32_f16 v[44:47], v[144:147], v[198:201], v[44:47]
	v_mfma_f32_16x16x32_f16 v[12:15], v[148:151], v[198:201], v[12:15]
	s_waitcnt lgkmcnt(2)
	v_mfma_f32_16x16x32_f16 v[104:107], v[136:139], v[202:205], v[104:107]
	v_mfma_f32_16x16x32_f16 v[72:75], v[140:143], v[202:205], v[72:75]
	v_mfma_f32_16x16x32_f16 v[40:43], v[144:147], v[202:205], v[40:43]
	v_mfma_f32_16x16x32_f16 v[8:11], v[148:151], v[202:205], v[8:11]
	s_waitcnt lgkmcnt(1)
	v_mfma_f32_16x16x32_f16 v[100:103], v[136:139], v[222:225], v[100:103]
	v_mfma_f32_16x16x32_f16 v[68:71], v[140:143], v[222:225], v[68:71]
	v_mfma_f32_16x16x32_f16 v[36:39], v[144:147], v[222:225], v[36:39]
	v_mfma_f32_16x16x32_f16 v[4:7], v[148:151], v[222:225], v[4:7]
	s_waitcnt lgkmcnt(0)
	v_mfma_f32_16x16x32_f16 v[96:99], v[136:139], v[226:229], v[96:99]
	v_mfma_f32_16x16x32_f16 v[64:67], v[140:143], v[226:229], v[64:67]
	v_mfma_f32_16x16x32_f16 v[32:35], v[144:147], v[226:229], v[32:35]
	v_mfma_f32_16x16x32_f16 v[0:3], v[148:151], v[226:229], v[0:3]
	s_add_u32 s18, s18, 128
	s_addc_u32 s19, s19, 0
	s_add_i32 s10, s10, 1
	s_cmp_lt_u32 s10, 10
	s_cbranch_scc1 .Lgin_loop
	s_waitcnt vmcnt(4)
	s_barrier
	ds_read_b128 v[230:233], v175 offset:0
	ds_read_b128 v[234:237], v175 offset:2048
	ds_read_b128 v[238:241], v175 offset:4096
	ds_read_b128 v[242:245], v175 offset:6144
	ds_read_b128 v[136:139], v177 offset:0
	ds_read_b128 v[140:143], v177 offset:2048
	ds_read_b128 v[144:147], v177 offset:4096
	ds_read_b128 v[148:151], v177 offset:6144
	ds_read_b128 v[182:185], v176 offset:16384
	ds_read_b128 v[186:189], v176 offset:18432
	ds_read_b128 v[190:193], v176 offset:20480
	ds_read_b128 v[194:197], v176 offset:22528
	s_add_u32 m0, s11, 0xc000
	s_waitcnt lgkmcnt(3)
	v_mfma_f32_16x16x32_f16 v[124:127], v[230:233], v[182:185], v[124:127]
	v_mfma_f32_16x16x32_f16 v[92:95], v[234:237], v[182:185], v[92:95]
	v_mfma_f32_16x16x32_f16 v[60:63], v[238:241], v[182:185], v[60:63]
	v_mfma_f32_16x16x32_f16 v[28:31], v[242:245], v[182:185], v[28:31]
	global_load_lds_dwordx4 v128, s[6:7] sc1
	s_barrier
	ds_read_b128 v[198:201], v178 offset:16384
	ds_read_b128 v[202:205], v178 offset:18432
	ds_read_b128 v[222:225], v178 offset:20480
	ds_read_b128 v[226:229], v178 offset:22528
	s_add_u32 m0, s11, 0xd000
	s_waitcnt lgkmcnt(6)
	v_mfma_f32_16x16x32_f16 v[120:123], v[230:233], v[186:189], v[120:123]
	v_mfma_f32_16x16x32_f16 v[88:91], v[234:237], v[186:189], v[88:91]
	v_mfma_f32_16x16x32_f16 v[56:59], v[238:241], v[186:189], v[56:59]
	v_mfma_f32_16x16x32_f16 v[24:27], v[242:245], v[186:189], v[24:27]
	global_load_lds_dwordx4 v129, s[6:7] sc1
	s_add_u32 m0, s11, 0xe000
	s_waitcnt lgkmcnt(5)
	v_mfma_f32_16x16x32_f16 v[116:119], v[230:233], v[190:193], v[116:119]
	v_mfma_f32_16x16x32_f16 v[84:87], v[234:237], v[190:193], v[84:87]
	v_mfma_f32_16x16x32_f16 v[52:55], v[238:241], v[190:193], v[52:55]
	v_mfma_f32_16x16x32_f16 v[20:23], v[242:245], v[190:193], v[20:23]
	global_load_lds_dwordx4 v132, s[6:7] sc1
	s_add_u32 m0, s11, 0xf000
	s_waitcnt lgkmcnt(4)
	v_mfma_f32_16x16x32_f16 v[112:115], v[230:233], v[194:197], v[112:115]
	v_mfma_f32_16x16x32_f16 v[80:83], v[234:237], v[194:197], v[80:83]
	v_mfma_f32_16x16x32_f16 v[48:51], v[238:241], v[194:197], v[48:51]
	v_mfma_f32_16x16x32_f16 v[16:19], v[242:245], v[194:197], v[16:19]
	global_load_lds_dwordx4 v133, s[6:7] sc1
	s_add_u32 m0, s11, 0x0
	s_waitcnt lgkmcnt(3)
	v_mfma_f32_16x16x32_f16 v[124:127], v[136:139], v[198:201], v[124:127]
	v_mfma_f32_16x16x32_f16 v[92:95], v[140:143], v[198:201], v[92:95]
	v_mfma_f32_16x16x32_f16 v[60:63], v[144:147], v[198:201], v[60:63]
	v_mfma_f32_16x16x32_f16 v[28:31], v[148:151], v[198:201], v[28:31]
	global_load_lds_dwordx4 v128, s[4:5] sc1
	s_add_u32 m0, s11, 0x1000
	s_waitcnt lgkmcnt(2)
	v_mfma_f32_16x16x32_f16 v[120:123], v[136:139], v[202:205], v[120:123]
	v_mfma_f32_16x16x32_f16 v[88:91], v[140:143], v[202:205], v[88:91]
	v_mfma_f32_16x16x32_f16 v[56:59], v[144:147], v[202:205], v[56:59]
	v_mfma_f32_16x16x32_f16 v[24:27], v[148:151], v[202:205], v[24:27]
	global_load_lds_dwordx4 v129, s[4:5] sc1
	s_add_u32 m0, s11, 0x2000
	s_waitcnt lgkmcnt(1)
	v_mfma_f32_16x16x32_f16 v[116:119], v[136:139], v[222:225], v[116:119]
	v_mfma_f32_16x16x32_f16 v[84:87], v[140:143], v[222:225], v[84:87]
	v_mfma_f32_16x16x32_f16 v[52:55], v[144:147], v[222:225], v[52:55]
	v_mfma_f32_16x16x32_f16 v[20:23], v[148:151], v[222:225], v[20:23]
	global_load_lds_dwordx4 v130, s[4:5] sc1
	s_add_u32 m0, s11, 0x3000
	s_waitcnt lgkmcnt(0)
	v_mfma_f32_16x16x32_f16 v[112:115], v[136:139], v[226:229], v[112:115]
	v_mfma_f32_16x16x32_f16 v[80:83], v[140:143], v[226:229], v[80:83]
	v_mfma_f32_16x16x32_f16 v[48:51], v[144:147], v[226:229], v[48:51]
	v_mfma_f32_16x16x32_f16 v[16:19], v[148:151], v[226:229], v[16:19]
	global_load_lds_dwordx4 v131, s[4:5] sc1
	s_add_u32 s6, s6, 128
	s_addc_u32 s7, s7, 0
	s_add_u32 s4, s4, 128
	s_addc_u32 s5, s5, 0
	s_waitcnt vmcnt(8)
	s_barrier
	ds_read_b128 v[182:185], v176 offset:32768
	ds_read_b128 v[186:189], v176 offset:34816
	ds_read_b128 v[190:193], v176 offset:36864
	ds_read_b128 v[194:197], v176 offset:38912
	ds_read_b128 v[198:201], v178 offset:32768
	ds_read_b128 v[202:205], v178 offset:34816
	ds_read_b128 v[222:225], v178 offset:36864
	ds_read_b128 v[226:229], v178 offset:38912
	s_add_u32 m0, s11, 0x4000
	s_waitcnt lgkmcnt(7)
	v_mfma_f32_16x16x32_f16 v[108:111], v[230:233], v[182:185], v[108:111]
	v_mfma_f32_16x16x32_f16 v[76:79], v[234:237], v[182:185], v[76:79]
	v_mfma_f32_16x16x32_f16 v[44:47], v[238:241], v[182:185], v[44:47]
	v_mfma_f32_16x16x32_f16 v[12:15], v[242:245], v[182:185], v[12:15]
	global_load_lds_dwordx4 v128, s[18:19] sc1
	s_add_u32 m0, s11, 0x5000
	s_waitcnt lgkmcnt(6)
	v_mfma_f32_16x16x32_f16 v[104:107], v[230:233], v[186:189], v[104:107]
	v_mfma_f32_16x16x32_f16 v[72:75], v[234:237], v[186:189], v[72:75]
	v_mfma_f32_16x16x32_f16 v[40:43], v[238:241], v[186:189], v[40:43]
	v_mfma_f32_16x16x32_f16 v[8:11], v[242:245], v[186:189], v[8:11]
	global_load_lds_dwordx4 v129, s[18:19] sc1
	s_add_u32 m0, s11, 0x6000
	s_waitcnt lgkmcnt(5)
	v_mfma_f32_16x16x32_f16 v[100:103], v[230:233], v[190:193], v[100:103]
	v_mfma_f32_16x16x32_f16 v[68:71], v[234:237], v[190:193], v[68:71]
	v_mfma_f32_16x16x32_f16 v[36:39], v[238:241], v[190:193], v[36:39]
	v_mfma_f32_16x16x32_f16 v[4:7], v[242:245], v[190:193], v[4:7]
	global_load_lds_dwordx4 v132, s[18:19] sc1
	s_add_u32 m0, s11, 0x7000
	s_waitcnt lgkmcnt(4)
	v_mfma_f32_16x16x32_f16 v[96:99], v[230:233], v[194:197], v[96:99]
	v_mfma_f32_16x16x32_f16 v[64:67], v[234:237], v[194:197], v[64:67]
	v_mfma_f32_16x16x32_f16 v[32:35], v[238:241], v[194:197], v[32:35]
	v_mfma_f32_16x16x32_f16 v[0:3], v[242:245], v[194:197], v[0:3]
	global_load_lds_dwordx4 v133, s[18:19] sc1
	s_waitcnt lgkmcnt(3)
	v_mfma_f32_16x16x32_f16 v[108:111], v[136:139], v[198:201], v[108:111]
	v_mfma_f32_16x16x32_f16 v[76:79], v[140:143], v[198:201], v[76:79]
	v_mfma_f32_16x16x32_f16 v[44:47], v[144:147], v[198:201], v[44:47]
	v_mfma_f32_16x16x32_f16 v[12:15], v[148:151], v[198:201], v[12:15]
	s_waitcnt lgkmcnt(2)
	v_mfma_f32_16x16x32_f16 v[104:107], v[136:139], v[202:205], v[104:107]
	v_mfma_f32_16x16x32_f16 v[72:75], v[140:143], v[202:205], v[72:75]
	v_mfma_f32_16x16x32_f16 v[40:43], v[144:147], v[202:205], v[40:43]
	v_mfma_f32_16x16x32_f16 v[8:11], v[148:151], v[202:205], v[8:11]
	s_waitcnt lgkmcnt(1)
	v_mfma_f32_16x16x32_f16 v[100:103], v[136:139], v[222:225], v[100:103]
	v_mfma_f32_16x16x32_f16 v[68:71], v[140:143], v[222:225], v[68:71]
	v_mfma_f32_16x16x32_f16 v[36:39], v[144:147], v[222:225], v[36:39]
	v_mfma_f32_16x16x32_f16 v[4:7], v[148:151], v[222:225], v[4:7]
	s_waitcnt lgkmcnt(0)
	v_mfma_f32_16x16x32_f16 v[96:99], v[136:139], v[226:229], v[96:99]
	v_mfma_f32_16x16x32_f16 v[64:67], v[140:143], v[226:229], v[64:67]
	v_mfma_f32_16x16x32_f16 v[32:35], v[144:147], v[226:229], v[32:35]
	v_mfma_f32_16x16x32_f16 v[0:3], v[148:151], v[226:229], v[0:3]
	s_add_u32 s18, s18, 128
	s_addc_u32 s19, s19, 0
	s_waitcnt vmcnt(4)
	s_barrier
	ds_read_b128 v[230:233], v175 offset:0
	ds_read_b128 v[234:237], v175 offset:2048
	ds_read_b128 v[238:241], v175 offset:4096
	ds_read_b128 v[242:245], v175 offset:6144
	ds_read_b128 v[136:139], v177 offset:0
	ds_read_b128 v[140:143], v177 offset:2048
	ds_read_b128 v[144:147], v177 offset:4096
	ds_read_b128 v[148:151], v177 offset:6144
	ds_read_b128 v[182:185], v176 offset:49152
	ds_read_b128 v[186:189], v176 offset:51200
	ds_read_b128 v[190:193], v176 offset:53248
	ds_read_b128 v[194:197], v176 offset:55296
	s_waitcnt lgkmcnt(3)
	v_mfma_f32_16x16x32_f16 v[124:127], v[230:233], v[182:185], v[124:127]
	v_mfma_f32_16x16x32_f16 v[92:95], v[234:237], v[182:185], v[92:95]
	v_mfma_f32_16x16x32_f16 v[60:63], v[238:241], v[182:185], v[60:63]
	v_mfma_f32_16x16x32_f16 v[28:31], v[242:245], v[182:185], v[28:31]
	s_barrier
	ds_read_b128 v[198:201], v178 offset:49152
	ds_read_b128 v[202:205], v178 offset:51200
	ds_read_b128 v[222:225], v178 offset:53248
	ds_read_b128 v[226:229], v178 offset:55296
	s_waitcnt lgkmcnt(6)
	v_mfma_f32_16x16x32_f16 v[120:123], v[230:233], v[186:189], v[120:123]
	v_mfma_f32_16x16x32_f16 v[88:91], v[234:237], v[186:189], v[88:91]
	v_mfma_f32_16x16x32_f16 v[56:59], v[238:241], v[186:189], v[56:59]
	v_mfma_f32_16x16x32_f16 v[24:27], v[242:245], v[186:189], v[24:27]
	s_waitcnt lgkmcnt(5)
	v_mfma_f32_16x16x32_f16 v[116:119], v[230:233], v[190:193], v[116:119]
	v_mfma_f32_16x16x32_f16 v[84:87], v[234:237], v[190:193], v[84:87]
	v_mfma_f32_16x16x32_f16 v[52:55], v[238:241], v[190:193], v[52:55]
	v_mfma_f32_16x16x32_f16 v[20:23], v[242:245], v[190:193], v[20:23]
	s_waitcnt lgkmcnt(4)
	v_mfma_f32_16x16x32_f16 v[112:115], v[230:233], v[194:197], v[112:115]
	v_mfma_f32_16x16x32_f16 v[80:83], v[234:237], v[194:197], v[80:83]
	v_mfma_f32_16x16x32_f16 v[48:51], v[238:241], v[194:197], v[48:51]
	v_mfma_f32_16x16x32_f16 v[16:19], v[242:245], v[194:197], v[16:19]
	s_waitcnt lgkmcnt(3)
	v_mfma_f32_16x16x32_f16 v[124:127], v[136:139], v[198:201], v[124:127]
	v_mfma_f32_16x16x32_f16 v[92:95], v[140:143], v[198:201], v[92:95]
	v_mfma_f32_16x16x32_f16 v[60:63], v[144:147], v[198:201], v[60:63]
	v_mfma_f32_16x16x32_f16 v[28:31], v[148:151], v[198:201], v[28:31]
	s_waitcnt lgkmcnt(2)
	v_mfma_f32_16x16x32_f16 v[120:123], v[136:139], v[202:205], v[120:123]
	v_mfma_f32_16x16x32_f16 v[88:91], v[140:143], v[202:205], v[88:91]
	v_mfma_f32_16x16x32_f16 v[56:59], v[144:147], v[202:205], v[56:59]
	v_mfma_f32_16x16x32_f16 v[24:27], v[148:151], v[202:205], v[24:27]
	s_waitcnt lgkmcnt(1)
	v_mfma_f32_16x16x32_f16 v[116:119], v[136:139], v[222:225], v[116:119]
	v_mfma_f32_16x16x32_f16 v[84:87], v[140:143], v[222:225], v[84:87]
	v_mfma_f32_16x16x32_f16 v[52:55], v[144:147], v[222:225], v[52:55]
	v_mfma_f32_16x16x32_f16 v[20:23], v[148:151], v[222:225], v[20:23]
	s_waitcnt lgkmcnt(0)
	v_mfma_f32_16x16x32_f16 v[112:115], v[136:139], v[226:229], v[112:115]
	v_mfma_f32_16x16x32_f16 v[80:83], v[140:143], v[226:229], v[80:83]
	v_mfma_f32_16x16x32_f16 v[48:51], v[144:147], v[226:229], v[48:51]
	v_mfma_f32_16x16x32_f16 v[16:19], v[148:151], v[226:229], v[16:19]
	s_waitcnt vmcnt(0)
	s_barrier
	ds_read_b128 v[182:185], v176 offset:16384
	ds_read_b128 v[186:189], v176 offset:18432
	ds_read_b128 v[190:193], v176 offset:20480
	ds_read_b128 v[194:197], v176 offset:22528
	ds_read_b128 v[198:201], v178 offset:16384
	ds_read_b128 v[202:205], v178 offset:18432
	ds_read_b128 v[222:225], v178 offset:20480
	ds_read_b128 v[226:229], v178 offset:22528
	s_waitcnt lgkmcnt(7)
	v_mfma_f32_16x16x32_f16 v[108:111], v[230:233], v[182:185], v[108:111]
	v_mfma_f32_16x16x32_f16 v[76:79], v[234:237], v[182:185], v[76:79]
	v_mfma_f32_16x16x32_f16 v[44:47], v[238:241], v[182:185], v[44:47]
	v_mfma_f32_16x16x32_f16 v[12:15], v[242:245], v[182:185], v[12:15]
	s_waitcnt lgkmcnt(6)
	v_mfma_f32_16x16x32_f16 v[104:107], v[230:233], v[186:189], v[104:107]
	v_mfma_f32_16x16x32_f16 v[72:75], v[234:237], v[186:189], v[72:75]
	v_mfma_f32_16x16x32_f16 v[40:43], v[238:241], v[186:189], v[40:43]
	v_mfma_f32_16x16x32_f16 v[8:11], v[242:245], v[186:189], v[8:11]
	s_waitcnt lgkmcnt(5)
	v_mfma_f32_16x16x32_f16 v[100:103], v[230:233], v[190:193], v[100:103]
	v_mfma_f32_16x16x32_f16 v[68:71], v[234:237], v[190:193], v[68:71]
	v_mfma_f32_16x16x32_f16 v[36:39], v[238:241], v[190:193], v[36:39]
	v_mfma_f32_16x16x32_f16 v[4:7], v[242:245], v[190:193], v[4:7]
	s_waitcnt lgkmcnt(4)
	v_mfma_f32_16x16x32_f16 v[96:99], v[230:233], v[194:197], v[96:99]
	v_mfma_f32_16x16x32_f16 v[64:67], v[234:237], v[194:197], v[64:67]
	v_mfma_f32_16x16x32_f16 v[32:35], v[238:241], v[194:197], v[32:35]
	v_mfma_f32_16x16x32_f16 v[0:3], v[242:245], v[194:197], v[0:3]
	s_waitcnt lgkmcnt(3)
	v_mfma_f32_16x16x32_f16 v[108:111], v[136:139], v[198:201], v[108:111]
	v_mfma_f32_16x16x32_f16 v[76:79], v[140:143], v[198:201], v[76:79]
	v_mfma_f32_16x16x32_f16 v[44:47], v[144:147], v[198:201], v[44:47]
	v_mfma_f32_16x16x32_f16 v[12:15], v[148:151], v[198:201], v[12:15]
	s_waitcnt lgkmcnt(2)
	v_mfma_f32_16x16x32_f16 v[104:107], v[136:139], v[202:205], v[104:107]
	v_mfma_f32_16x16x32_f16 v[72:75], v[140:143], v[202:205], v[72:75]
	v_mfma_f32_16x16x32_f16 v[40:43], v[144:147], v[202:205], v[40:43]
	v_mfma_f32_16x16x32_f16 v[8:11], v[148:151], v[202:205], v[8:11]
	s_waitcnt lgkmcnt(1)
	v_mfma_f32_16x16x32_f16 v[100:103], v[136:139], v[222:225], v[100:103]
	v_mfma_f32_16x16x32_f16 v[68:71], v[140:143], v[222:225], v[68:71]
	v_mfma_f32_16x16x32_f16 v[36:39], v[144:147], v[222:225], v[36:39]
	v_mfma_f32_16x16x32_f16 v[4:7], v[148:151], v[222:225], v[4:7]
	s_waitcnt lgkmcnt(0)
	v_mfma_f32_16x16x32_f16 v[96:99], v[136:139], v[226:229], v[96:99]
	v_mfma_f32_16x16x32_f16 v[64:67], v[140:143], v[226:229], v[64:67]
	v_mfma_f32_16x16x32_f16 v[32:35], v[144:147], v[226:229], v[32:35]
	v_mfma_f32_16x16x32_f16 v[0:3], v[148:151], v[226:229], v[0:3]
	s_nop 7
	s_cmpk_lt_u32 s9, 0x620
	s_cbranch_scc0 .Lgin_cls_lat
	s_cmp_lt_u32 s16, 4
	s_cbranch_scc1 .Lgin_plain
	s_sub_u32 s4, s16, 8
	s_cmp_lt_u32 s4, 28
	s_cbranch_scc1 .Lgin_plain
	s_sub_u32 s4, s16, 45
	s_cmp_lt_u32 s4, 3
	s_cbranch_scc1 .Lgin_plain
	s_sub_u32 s4, s16, 4
	s_cmp_lt_u32 s4, 2
	s_cbranch_scc1 .Lgin_kvar
	s_sub_u32 s4, s16, 37
	s_cmp_lt_u32 s4, 3
	s_cbranch_scc1 .Lgin_kvar
	s_sub_u32 s4, s16, 6
	s_cmp_lt_u32 s4, 2
	s_cbranch_scc1 .Lgin_vvar
	s_sub_u32 s4, s16, 41
	s_cmp_lt_u32 s4, 3
	s_cbranch_scc1 .Lgin_vvar
	s_branch .Lgin_notplain

.LBB0_1352:
	s_lshr_b32 s4, s0, 4
	s_and_b32 s4, s4, 0x78
	s_and_b32 s5, s0, 7
	s_lshl_b32 s0, s0, 4
	s_or_b32 s4, s4, s5
	s_and_b32 s7, s0, 0x780
	s_lshl_b32 s4, s4, 7
	v_readfirstlane_b32 s8, v128
	v_readfirstlane_b32 s9, v129
	v_readfirstlane_b32 s10, v130
	v_readfirstlane_b32 s11, v131
	v_lshrrev_b32_e32 v198, 6, v171
	v_and_b32_e32 v199, 63, v171
	v_readfirstlane_b32 s12, v198
	s_lshl_b32 s16, s7, 12
	s_add_u32 s8, s8, s16
	s_addc_u32 s9, s9, 0
	s_lshl_b32 s16, s4, 12
	s_add_u32 s10, s10, s16
	s_addc_u32 s11, s11, 0
	s_add_u32 s14, s10, 0x20000
	s_addc_u32 s15, s11, 0
	v_lshrrev_b32_e32 v194, 4, v199
	v_and_b32_e32 v190, 7, v199
	v_lshrrev_b32_e32 v191, 3, v199
	s_and_b32 s16, s12, 1
	s_lshl_b32 s16, s16, 2
	v_or_b32_e32 v196, s16, v194
	v_xor_b32_e32 v190, v190, v196
	v_lshlrev_b32_e32 v190, 4, v190
	v_lshl_or_b32 v190, v191, 12, v190
	s_lshl_b32 s16, s12, 15
	v_add_u32_e32 v190, s16, v190
	v_add_u32_e32 v191, 0x20000, v190
	v_add_u32_e32 v192, 0x40000, v190
	v_add_u32_e32 v193, 0x60000, v190
	v_and_b32_e32 v198, 15, v199
	v_bfe_u32 v196, v198, 1, 3
	v_xor_b32_e32 v196, v196, v194
	v_lshlrev_b32_e32 v196, 4, v196
	v_lshl_or_b32 v196, v198, 7, v196
	s_and_b32 s16, s12, 1
	s_lshl_b32 s16, s16, 13
	v_add_u32_e32 v194, s16, v196
	s_lshr_b32 s17, s12, 1
	s_lshl_b32 s17, s17, 12
	s_add_u32 s17, s17, 0x8000
	v_add_u32_e32 v196, s17, v196
	v_xor_b32_e32 v195, 64, v194
	v_xor_b32_e32 v197, 64, v196
	s_lshl_b32 s12, s12, 10
	s_barrier
	s_lshl_b32 s16, s4, 13
	s_lshl_b32 s17, s7, 2
	s_add_u32 s16, s16, s17
	s_add_u32 s18, s94, s16
	s_addc_u32 s19, s95, 0
	v_readlane_b32 s36, v253, 0
	v_readlane_b32 s37, v253, 1
	v_readlane_b32 s40, v253, 2
	v_readlane_b32 s41, v253, 3
	s_cmpk_lt_u32 s4, 0x2000
	s_cselect_b32 s36, s36, s40
	s_cselect_b32 s37, s37, s41
	s_cselect_b32 s40, 0, 0x4000000
	s_sub_u32 s41, s16, s40
	s_add_u32 s36, s36, s41
	s_addc_u32 s37, s37, 0
	s_cmp_lg_u32 s46, 0
	s_cselect_b32 s36, s18, s36
	s_cselect_b32 s37, s19, s37
	s_sub_u32 s40, s4, 0x2000
	s_lshr_b32 s40, s40, 10
	s_add_u32 s40, s40, 1
	s_cmpk_lt_u32 s4, 0x2000
	s_cselect_b32 s40, 0, s40
	s_add_u32 s40, s40, s48
	s_mul_i32 s40, s40, 0x6000
	s_add_u32 s40, s40, 0x4000
	s_add_u32 s40, s40, s17
	v_readlane_b32 s38, v254, 45
	v_readlane_b32 s39, v254, 46
	s_add_u32 s38, s38, s40
	s_addc_u32 s39, s39, 0
	v_and_b32_e32 v150, 15, v199
	v_lshrrev_b32_e32 v148, 4, v199
	s_lshr_b32 s40, s12, 11
	s_lshl_b32 s40, s40, 6
	v_add_u32_e32 v150, s40, v150
	s_bfe_u32 s41, s12, 0x1000a
	s_lshl_b32 s41, s41, 6
	v_lshl_add_u32 v148, v148, 2, s41
	v_lshlrev_b32_e32 v148, 2, v148
	v_lshl_add_u32 v150, v150, 13, v148
	v_add_u32_e32 v151, 0x20000, v150
	v_add_u32_e32 v152, 0x40000, v150
	v_add_u32_e32 v153, 0x60000, v150
	s_add_u32 m0, s12, 0x8000
	s_nop 0
	global_load_lds_dwordx4 v190, s[10:11] sc1
	s_add_u32 m0, s12, 0x9000
	s_nop 0
	global_load_lds_dwordx4 v192, s[10:11] sc1
	s_add_u32 s10, s10, 128
	s_addc_u32 s11, s11, 0
	s_add_u32 m0, s12, 0xa000
	s_nop 0
	global_load_lds_dwordx4 v190, s[14:15] sc1
	s_add_u32 m0, s12, 0xb000
	s_nop 0
	global_load_lds_dwordx4 v192, s[14:15] sc1
	s_add_u32 s14, s14, 128
	s_addc_u32 s15, s15, 0
	s_add_u32 m0, s12, 0x0
	s_nop 0
	global_load_lds_dwordx4 v190, s[8:9] sc1
	s_add_u32 m0, s12, 0x1000
	s_nop 0
	global_load_lds_dwordx4 v191, s[8:9] sc1
	s_add_u32 m0, s12, 0x2000
	s_nop 0
	global_load_lds_dwordx4 v192, s[8:9] sc1
	s_add_u32 m0, s12, 0x3000
	s_nop 0
	global_load_lds_dwordx4 v193, s[8:9] sc1
	s_add_u32 s8, s8, 128
	s_addc_u32 s9, s9, 0
	s_add_u32 m0, s12, 0xc000
	s_nop 0
	global_load_lds_dwordx4 v190, s[10:11] sc1
	s_add_u32 m0, s12, 0xd000
	s_nop 0
	global_load_lds_dwordx4 v192, s[10:11] sc1
	s_add_u32 s10, s10, 128
	s_addc_u32 s11, s11, 0
	s_add_u32 m0, s12, 0xe000
	s_nop 0
	global_load_lds_dwordx4 v190, s[14:15] sc1
	s_add_u32 m0, s12, 0xf000
	s_nop 0
	global_load_lds_dwordx4 v192, s[14:15] sc1
	s_add_u32 s14, s14, 128
	s_addc_u32 s15, s15, 0
	s_add_u32 m0, s12, 0x4000
	s_nop 0
	global_load_lds_dwordx4 v190, s[8:9] sc1
	s_add_u32 m0, s12, 0x5000
	s_nop 0
	global_load_lds_dwordx4 v191, s[8:9] sc1
	s_add_u32 m0, s12, 0x6000
	s_nop 0
	global_load_lds_dwordx4 v192, s[8:9] sc1
	s_add_u32 m0, s12, 0x7000
	s_nop 0
	global_load_lds_dwordx4 v193, s[8:9] sc1
	s_add_u32 s8, s8, 128
	s_addc_u32 s9, s9, 0
	v_mov_b32_e32 v0, 0
	v_mov_b32_e32 v1, v0
	v_mov_b32_e32 v2, v0
	v_mov_b32_e32 v3, v0
	v_mov_b32_e32 v4, v0
	v_mov_b32_e32 v5, v0
	v_mov_b32_e32 v6, v0
	v_mov_b32_e32 v7, v0
	v_mov_b32_e32 v8, v0
	v_mov_b32_e32 v9, v0
	v_mov_b32_e32 v10, v0
	v_mov_b32_e32 v11, v0
	v_mov_b32_e32 v12, v0
	v_mov_b32_e32 v13, v0
	v_mov_b32_e32 v14, v0
	v_mov_b32_e32 v15, v0
	v_mov_b32_e32 v16, v0
	v_mov_b32_e32 v17, v0
	v_mov_b32_e32 v18, v0
	v_mov_b32_e32 v19, v0
	v_mov_b32_e32 v20, v0
	v_mov_b32_e32 v21, v0
	v_mov_b32_e32 v22, v0
	v_mov_b32_e32 v23, v0
	v_mov_b32_e32 v24, v0
	v_mov_b32_e32 v25, v0
	v_mov_b32_e32 v26, v0
	v_mov_b32_e32 v27, v0
	v_mov_b32_e32 v28, v0
	v_mov_b32_e32 v29, v0
	v_mov_b32_e32 v30, v0
	v_mov_b32_e32 v31, v0
	v_mov_b32_e32 v32, v0
	v_mov_b32_e32 v33, v0
	v_mov_b32_e32 v34, v0
	v_mov_b32_e32 v35, v0
	v_mov_b32_e32 v36, v0
	v_mov_b32_e32 v37, v0
	v_mov_b32_e32 v38, v0
	v_mov_b32_e32 v39, v0
	v_mov_b32_e32 v40, v0
	v_mov_b32_e32 v41, v0
	v_mov_b32_e32 v42, v0
	v_mov_b32_e32 v43, v0
	v_mov_b32_e32 v44, v0
	v_mov_b32_e32 v45, v0
	v_mov_b32_e32 v46, v0
	v_mov_b32_e32 v47, v0
	v_mov_b32_e32 v48, v0
	v_mov_b32_e32 v49, v0
	v_mov_b32_e32 v50, v0
	v_mov_b32_e32 v51, v0
	v_mov_b32_e32 v52, v0
	v_mov_b32_e32 v53, v0
	v_mov_b32_e32 v54, v0
	v_mov_b32_e32 v55, v0
	v_mov_b32_e32 v56, v0
	v_mov_b32_e32 v57, v0
	v_mov_b32_e32 v58, v0
	v_mov_b32_e32 v59, v0
	v_mov_b32_e32 v124, v0
	v_mov_b32_e32 v125, v0
	v_mov_b32_e32 v126, v0
	v_mov_b32_e32 v127, v0
	s_mov_b32 s13, 0
.Lgout_loop:
	s_waitcnt vmcnt(8)
	s_barrier
	ds_read_b128 v[90:93], v194 offset:0
	ds_read_b128 v[94:97], v194 offset:2048
	ds_read_b128 v[98:101], v194 offset:4096
	ds_read_b128 v[102:105], v194 offset:6144
	ds_read_b128 v[132:135], v196 offset:0
	ds_read_b128 v[136:139], v196 offset:2048
	ds_read_b128 v[106:109], v195 offset:0
	ds_read_b128 v[110:113], v195 offset:2048
	ds_read_b128 v[114:117], v195 offset:4096
	ds_read_b128 v[118:121], v195 offset:6144
	ds_read_b128 v[140:143], v197 offset:0
	ds_read_b128 v[144:147], v197 offset:2048
	s_waitcnt lgkmcnt(7)
	s_add_u32 m0, s12, 0x10000
	v_mfma_f32_16x16x32_f16 v[124:127], v[90:93], v[132:135], v[124:127]
	global_load_lds_dwordx4 v190, s[10:11] sc1
	v_mfma_f32_16x16x32_f16 v[44:47], v[94:97], v[132:135], v[44:47]
	v_mfma_f32_16x16x32_f16 v[28:31], v[98:101], v[132:135], v[28:31]
	v_mfma_f32_16x16x32_f16 v[12:15], v[102:105], v[132:135], v[12:15]
	s_waitcnt lgkmcnt(6)
	s_add_u32 m0, s12, 0x11000
	v_mfma_f32_16x16x32_f16 v[56:59], v[90:93], v[136:139], v[56:59]
	global_load_lds_dwordx4 v192, s[10:11] sc1
	v_mfma_f32_16x16x32_f16 v[40:43], v[94:97], v[136:139], v[40:43]
	v_mfma_f32_16x16x32_f16 v[24:27], v[98:101], v[136:139], v[24:27]
	v_mfma_f32_16x16x32_f16 v[8:11], v[102:105], v[136:139], v[8:11]
	s_waitcnt lgkmcnt(1)
	v_mfma_f32_16x16x32_f16 v[124:127], v[106:109], v[140:143], v[124:127]
	v_mfma_f32_16x16x32_f16 v[44:47], v[110:113], v[140:143], v[44:47]
	v_mfma_f32_16x16x32_f16 v[28:31], v[114:117], v[140:143], v[28:31]
	v_mfma_f32_16x16x32_f16 v[12:15], v[118:121], v[140:143], v[12:15]
	s_waitcnt lgkmcnt(0)
	v_mfma_f32_16x16x32_f16 v[56:59], v[106:109], v[144:147], v[56:59]
	v_mfma_f32_16x16x32_f16 v[40:43], v[110:113], v[144:147], v[40:43]
	v_mfma_f32_16x16x32_f16 v[24:27], v[114:117], v[144:147], v[24:27]
	v_mfma_f32_16x16x32_f16 v[8:11], v[118:121], v[144:147], v[8:11]
	s_add_u32 s10, s10, 128
	s_addc_u32 s11, s11, 0
	s_barrier
	ds_read_b128 v[174:177], v196 offset:8192
	ds_read_b128 v[178:181], v196 offset:10240
	ds_read_b128 v[182:185], v197 offset:8192
	ds_read_b128 v[186:189], v197 offset:10240
	s_waitcnt lgkmcnt(3)
	s_add_u32 m0, s12, 0x8000
	v_mfma_f32_16x16x32_f16 v[52:55], v[90:93], v[174:177], v[52:55]
	global_load_lds_dwordx4 v190, s[14:15] sc1
	v_mfma_f32_16x16x32_f16 v[36:39], v[94:97], v[174:177], v[36:39]
	s_add_u32 m0, s12, 0x9000
	v_mfma_f32_16x16x32_f16 v[20:23], v[98:101], v[174:177], v[20:23]
	global_load_lds_dwordx4 v192, s[14:15] sc1
	v_mfma_f32_16x16x32_f16 v[4:7], v[102:105], v[174:177], v[4:7]
	s_waitcnt lgkmcnt(2)
	s_add_u32 m0, s12, 0x0
	v_mfma_f32_16x16x32_f16 v[48:51], v[90:93], v[178:181], v[48:51]
	global_load_lds_dwordx4 v190, s[8:9] sc1
	v_mfma_f32_16x16x32_f16 v[32:35], v[94:97], v[178:181], v[32:35]
	s_add_u32 m0, s12, 0x1000
	v_mfma_f32_16x16x32_f16 v[16:19], v[98:101], v[178:181], v[16:19]
	global_load_lds_dwordx4 v191, s[8:9] sc1
	v_mfma_f32_16x16x32_f16 v[0:3], v[102:105], v[178:181], v[0:3]
	s_waitcnt lgkmcnt(1)
	s_add_u32 m0, s12, 0x2000
	v_mfma_f32_16x16x32_f16 v[52:55], v[106:109], v[182:185], v[52:55]
	global_load_lds_dwordx4 v192, s[8:9] sc1
	v_mfma_f32_16x16x32_f16 v[36:39], v[110:113], v[182:185], v[36:39]
	v_mfma_f32_16x16x32_f16 v[20:23], v[114:117], v[182:185], v[20:23]
	v_mfma_f32_16x16x32_f16 v[4:7], v[118:121], v[182:185], v[4:7]
	s_waitcnt lgkmcnt(0)
	s_add_u32 m0, s12, 0x3000
	v_mfma_f32_16x16x32_f16 v[48:51], v[106:109], v[186:189], v[48:51]
	global_load_lds_dwordx4 v193, s[8:9] sc1
	v_mfma_f32_16x16x32_f16 v[32:35], v[110:113], v[186:189], v[32:35]
	v_mfma_f32_16x16x32_f16 v[16:19], v[114:117], v[186:189], v[16:19]
	v_mfma_f32_16x16x32_f16 v[0:3], v[118:121], v[186:189], v[0:3]
	s_add_u32 s14, s14, 128
	s_addc_u32 s15, s15, 0
	s_add_u32 s8, s8, 128
	s_addc_u32 s9, s9, 0
	s_waitcnt vmcnt(8)
	s_barrier
	ds_read_b128 v[90:93], v194 offset:16384
	ds_read_b128 v[94:97], v194 offset:18432
	ds_read_b128 v[98:101], v194 offset:20480
	ds_read_b128 v[102:105], v194 offset:22528
	ds_read_b128 v[132:135], v196 offset:16384
	ds_read_b128 v[136:139], v196 offset:18432
	ds_read_b128 v[106:109], v195 offset:16384
	ds_read_b128 v[110:113], v195 offset:18432
	ds_read_b128 v[114:117], v195 offset:20480
	ds_read_b128 v[118:121], v195 offset:22528
	ds_read_b128 v[140:143], v197 offset:16384
	ds_read_b128 v[144:147], v197 offset:18432
	s_waitcnt lgkmcnt(7)
	s_add_u32 m0, s12, 0xa000
	v_mfma_f32_16x16x32_f16 v[124:127], v[90:93], v[132:135], v[124:127]
	global_load_lds_dwordx4 v190, s[10:11] sc1
	v_mfma_f32_16x16x32_f16 v[44:47], v[94:97], v[132:135], v[44:47]
	v_mfma_f32_16x16x32_f16 v[28:31], v[98:101], v[132:135], v[28:31]
	v_mfma_f32_16x16x32_f16 v[12:15], v[102:105], v[132:135], v[12:15]
	s_waitcnt lgkmcnt(6)
	s_add_u32 m0, s12, 0xb000
	v_mfma_f32_16x16x32_f16 v[56:59], v[90:93], v[136:139], v[56:59]
	global_load_lds_dwordx4 v192, s[10:11] sc1
	v_mfma_f32_16x16x32_f16 v[40:43], v[94:97], v[136:139], v[40:43]
	v_mfma_f32_16x16x32_f16 v[24:27], v[98:101], v[136:139], v[24:27]
	v_mfma_f32_16x16x32_f16 v[8:11], v[102:105], v[136:139], v[8:11]
	s_waitcnt lgkmcnt(1)
	v_mfma_f32_16x16x32_f16 v[124:127], v[106:109], v[140:143], v[124:127]
	v_mfma_f32_16x16x32_f16 v[44:47], v[110:113], v[140:143], v[44:47]
	v_mfma_f32_16x16x32_f16 v[28:31], v[114:117], v[140:143], v[28:31]
	v_mfma_f32_16x16x32_f16 v[12:15], v[118:121], v[140:143], v[12:15]
	s_waitcnt lgkmcnt(0)
	v_mfma_f32_16x16x32_f16 v[56:59], v[106:109], v[144:147], v[56:59]
	v_mfma_f32_16x16x32_f16 v[40:43], v[110:113], v[144:147], v[40:43]
	v_mfma_f32_16x16x32_f16 v[24:27], v[114:117], v[144:147], v[24:27]
	v_mfma_f32_16x16x32_f16 v[8:11], v[118:121], v[144:147], v[8:11]
	s_add_u32 s10, s10, 128
	s_addc_u32 s11, s11, 0
	s_barrier
	ds_read_b128 v[174:177], v196 offset:24576
	ds_read_b128 v[178:181], v196 offset:26624
	ds_read_b128 v[182:185], v197 offset:24576
	ds_read_b128 v[186:189], v197 offset:26624
	s_waitcnt lgkmcnt(3)
	s_add_u32 m0, s12, 0xc000
	v_mfma_f32_16x16x32_f16 v[52:55], v[90:93], v[174:177], v[52:55]
	global_load_lds_dwordx4 v190, s[14:15] sc1
	v_mfma_f32_16x16x32_f16 v[36:39], v[94:97], v[174:177], v[36:39]
	s_add_u32 m0, s12, 0xd000
	v_mfma_f32_16x16x32_f16 v[20:23], v[98:101], v[174:177], v[20:23]
	global_load_lds_dwordx4 v192, s[14:15] sc1
	v_mfma_f32_16x16x32_f16 v[4:7], v[102:105], v[174:177], v[4:7]
	s_waitcnt lgkmcnt(2)
	s_add_u32 m0, s12, 0x4000
	v_mfma_f32_16x16x32_f16 v[48:51], v[90:93], v[178:181], v[48:51]
	global_load_lds_dwordx4 v190, s[8:9] sc1
	v_mfma_f32_16x16x32_f16 v[32:35], v[94:97], v[178:181], v[32:35]
	s_add_u32 m0, s12, 0x5000
	v_mfma_f32_16x16x32_f16 v[16:19], v[98:101], v[178:181], v[16:19]
	global_load_lds_dwordx4 v191, s[8:9] sc1
	v_mfma_f32_16x16x32_f16 v[0:3], v[102:105], v[178:181], v[0:3]
	s_waitcnt lgkmcnt(1)
	s_add_u32 m0, s12, 0x6000
	v_mfma_f32_16x16x32_f16 v[52:55], v[106:109], v[182:185], v[52:55]
	global_load_lds_dwordx4 v192, s[8:9] sc1
	v_mfma_f32_16x16x32_f16 v[36:39], v[110:113], v[182:185], v[36:39]
	v_mfma_f32_16x16x32_f16 v[20:23], v[114:117], v[182:185], v[20:23]
	v_mfma_f32_16x16x32_f16 v[4:7], v[118:121], v[182:185], v[4:7]
	s_waitcnt lgkmcnt(0)
	s_add_u32 m0, s12, 0x7000
	v_mfma_f32_16x16x32_f16 v[48:51], v[106:109], v[186:189], v[48:51]
	global_load_lds_dwordx4 v193, s[8:9] sc1
	v_mfma_f32_16x16x32_f16 v[32:35], v[110:113], v[186:189], v[32:35]
	v_mfma_f32_16x16x32_f16 v[16:19], v[114:117], v[186:189], v[16:19]
	v_mfma_f32_16x16x32_f16 v[0:3], v[118:121], v[186:189], v[0:3]
	s_add_u32 s14, s14, 128
	s_addc_u32 s15, s15, 0
	s_add_u32 s8, s8, 128
	s_addc_u32 s9, s9, 0
	s_waitcnt vmcnt(8)
	s_barrier
	ds_read_b128 v[90:93], v194 offset:0
	ds_read_b128 v[94:97], v194 offset:2048
	ds_read_b128 v[98:101], v194 offset:4096
	ds_read_b128 v[102:105], v194 offset:6144
	ds_read_b128 v[132:135], v196 offset:32768
	ds_read_b128 v[136:139], v196 offset:34816
	ds_read_b128 v[106:109], v195 offset:0
	ds_read_b128 v[110:113], v195 offset:2048
	ds_read_b128 v[114:117], v195 offset:4096
	ds_read_b128 v[118:121], v195 offset:6144
	ds_read_b128 v[140:143], v197 offset:32768
	ds_read_b128 v[144:147], v197 offset:34816
	s_waitcnt lgkmcnt(7)
	s_add_u32 m0, s12, 0xe000
	v_mfma_f32_16x16x32_f16 v[124:127], v[90:93], v[132:135], v[124:127]
	global_load_lds_dwordx4 v190, s[10:11] sc1
	v_mfma_f32_16x16x32_f16 v[44:47], v[94:97], v[132:135], v[44:47]
	v_mfma_f32_16x16x32_f16 v[28:31], v[98:101], v[132:135], v[28:31]
	v_mfma_f32_16x16x32_f16 v[12:15], v[102:105], v[132:135], v[12:15]
	s_waitcnt lgkmcnt(6)
	s_add_u32 m0, s12, 0xf000
	v_mfma_f32_16x16x32_f16 v[56:59], v[90:93], v[136:139], v[56:59]
	global_load_lds_dwordx4 v192, s[10:11] sc1
	v_mfma_f32_16x16x32_f16 v[40:43], v[94:97], v[136:139], v[40:43]
	v_mfma_f32_16x16x32_f16 v[24:27], v[98:101], v[136:139], v[24:27]
	v_mfma_f32_16x16x32_f16 v[8:11], v[102:105], v[136:139], v[8:11]
	s_waitcnt lgkmcnt(1)
	v_mfma_f32_16x16x32_f16 v[124:127], v[106:109], v[140:143], v[124:127]
	v_mfma_f32_16x16x32_f16 v[44:47], v[110:113], v[140:143], v[44:47]
	v_mfma_f32_16x16x32_f16 v[28:31], v[114:117], v[140:143], v[28:31]
	v_mfma_f32_16x16x32_f16 v[12:15], v[118:121], v[140:143], v[12:15]
	s_waitcnt lgkmcnt(0)
	v_mfma_f32_16x16x32_f16 v[56:59], v[106:109], v[144:147], v[56:59]
	v_mfma_f32_16x16x32_f16 v[40:43], v[110:113], v[144:147], v[40:43]
	v_mfma_f32_16x16x32_f16 v[24:27], v[114:117], v[144:147], v[24:27]
	v_mfma_f32_16x16x32_f16 v[8:11], v[118:121], v[144:147], v[8:11]
	s_add_u32 s10, s10, 128
	s_addc_u32 s11, s11, 0
	s_barrier
	ds_read_b128 v[174:177], v196 offset:0
	ds_read_b128 v[178:181], v196 offset:2048
	ds_read_b128 v[182:185], v197 offset:0
	ds_read_b128 v[186:189], v197 offset:2048
	s_waitcnt lgkmcnt(3)
	s_add_u32 m0, s12, 0x10000
	v_mfma_f32_16x16x32_f16 v[52:55], v[90:93], v[174:177], v[52:55]
	global_load_lds_dwordx4 v190, s[14:15] sc1
	v_mfma_f32_16x16x32_f16 v[36:39], v[94:97], v[174:177], v[36:39]
	s_add_u32 m0, s12, 0x11000
	v_mfma_f32_16x16x32_f16 v[20:23], v[98:101], v[174:177], v[20:23]
	global_load_lds_dwordx4 v192, s[14:15] sc1
	v_mfma_f32_16x16x32_f16 v[4:7], v[102:105], v[174:177], v[4:7]
	s_waitcnt lgkmcnt(2)
	s_add_u32 m0, s12, 0x0
	v_mfma_f32_16x16x32_f16 v[48:51], v[90:93], v[178:181], v[48:51]
	global_load_lds_dwordx4 v190, s[8:9] sc1
	v_mfma_f32_16x16x32_f16 v[32:35], v[94:97], v[178:181], v[32:35]
	s_add_u32 m0, s12, 0x1000
	v_mfma_f32_16x16x32_f16 v[16:19], v[98:101], v[178:181], v[16:19]
	global_load_lds_dwordx4 v191, s[8:9] sc1
	v_mfma_f32_16x16x32_f16 v[0:3], v[102:105], v[178:181], v[0:3]
	s_waitcnt lgkmcnt(1)
	s_add_u32 m0, s12, 0x2000
	v_mfma_f32_16x16x32_f16 v[52:55], v[106:109], v[182:185], v[52:55]
	global_load_lds_dwordx4 v192, s[8:9] sc1
	v_mfma_f32_16x16x32_f16 v[36:39], v[110:113], v[182:185], v[36:39]
	v_mfma_f32_16x16x32_f16 v[20:23], v[114:117], v[182:185], v[20:23]
	v_mfma_f32_16x16x32_f16 v[4:7], v[118:121], v[182:185], v[4:7]
	s_waitcnt lgkmcnt(0)
	s_add_u32 m0, s12, 0x3000
	v_mfma_f32_16x16x32_f16 v[48:51], v[106:109], v[186:189], v[48:51]
	global_load_lds_dwordx4 v193, s[8:9] sc1
	v_mfma_f32_16x16x32_f16 v[32:35], v[110:113], v[186:189], v[32:35]
	v_mfma_f32_16x16x32_f16 v[16:19], v[114:117], v[186:189], v[16:19]
	v_mfma_f32_16x16x32_f16 v[0:3], v[118:121], v[186:189], v[0:3]
	s_add_u32 s14, s14, 128
	s_addc_u32 s15, s15, 0
	s_add_u32 s8, s8, 128
	s_addc_u32 s9, s9, 0
	s_waitcnt vmcnt(8)
	s_barrier
	ds_read_b128 v[90:93], v194 offset:16384
	ds_read_b128 v[94:97], v194 offset:18432
	ds_read_b128 v[98:101], v194 offset:20480
	ds_read_b128 v[102:105], v194 offset:22528
	ds_read_b128 v[132:135], v196 offset:8192
	ds_read_b128 v[136:139], v196 offset:10240
	ds_read_b128 v[106:109], v195 offset:16384
	ds_read_b128 v[110:113], v195 offset:18432
	ds_read_b128 v[114:117], v195 offset:20480
	ds_read_b128 v[118:121], v195 offset:22528
	ds_read_b128 v[140:143], v197 offset:8192
	ds_read_b128 v[144:147], v197 offset:10240
	s_waitcnt lgkmcnt(7)
	s_add_u32 m0, s12, 0x8000
	v_mfma_f32_16x16x32_f16 v[124:127], v[90:93], v[132:135], v[124:127]
	global_load_lds_dwordx4 v190, s[10:11] sc1
	v_mfma_f32_16x16x32_f16 v[44:47], v[94:97], v[132:135], v[44:47]
	v_mfma_f32_16x16x32_f16 v[28:31], v[98:101], v[132:135], v[28:31]
	v_mfma_f32_16x16x32_f16 v[12:15], v[102:105], v[132:135], v[12:15]
	s_waitcnt lgkmcnt(6)
	s_add_u32 m0, s12, 0x9000
	v_mfma_f32_16x16x32_f16 v[56:59], v[90:93], v[136:139], v[56:59]
	global_load_lds_dwordx4 v192, s[10:11] sc1
	v_mfma_f32_16x16x32_f16 v[40:43], v[94:97], v[136:139], v[40:43]
	v_mfma_f32_16x16x32_f16 v[24:27], v[98:101], v[136:139], v[24:27]
	v_mfma_f32_16x16x32_f16 v[8:11], v[102:105], v[136:139], v[8:11]
	s_waitcnt lgkmcnt(1)
	v_mfma_f32_16x16x32_f16 v[124:127], v[106:109], v[140:143], v[124:127]
	v_mfma_f32_16x16x32_f16 v[44:47], v[110:113], v[140:143], v[44:47]
	v_mfma_f32_16x16x32_f16 v[28:31], v[114:117], v[140:143], v[28:31]
	v_mfma_f32_16x16x32_f16 v[12:15], v[118:121], v[140:143], v[12:15]
	s_waitcnt lgkmcnt(0)
	v_mfma_f32_16x16x32_f16 v[56:59], v[106:109], v[144:147], v[56:59]
	v_mfma_f32_16x16x32_f16 v[40:43], v[110:113], v[144:147], v[40:43]
	v_mfma_f32_16x16x32_f16 v[24:27], v[114:117], v[144:147], v[24:27]
	v_mfma_f32_16x16x32_f16 v[8:11], v[118:121], v[144:147], v[8:11]
	s_add_u32 s10, s10, 128
	s_addc_u32 s11, s11, 0
	s_barrier
	ds_read_b128 v[174:177], v196 offset:16384
	ds_read_b128 v[178:181], v196 offset:18432
	ds_read_b128 v[182:185], v197 offset:16384
	ds_read_b128 v[186:189], v197 offset:18432
	s_waitcnt lgkmcnt(3)
	s_add_u32 m0, s12, 0xa000
	v_mfma_f32_16x16x32_f16 v[52:55], v[90:93], v[174:177], v[52:55]
	global_load_lds_dwordx4 v190, s[14:15] sc1
	v_mfma_f32_16x16x32_f16 v[36:39], v[94:97], v[174:177], v[36:39]
	s_add_u32 m0, s12, 0xb000
	v_mfma_f32_16x16x32_f16 v[20:23], v[98:101], v[174:177], v[20:23]
	global_load_lds_dwordx4 v192, s[14:15] sc1
	v_mfma_f32_16x16x32_f16 v[4:7], v[102:105], v[174:177], v[4:7]
	s_waitcnt lgkmcnt(2)
	s_add_u32 m0, s12, 0x4000
	v_mfma_f32_16x16x32_f16 v[48:51], v[90:93], v[178:181], v[48:51]
	global_load_lds_dwordx4 v190, s[8:9] sc1
	v_mfma_f32_16x16x32_f16 v[32:35], v[94:97], v[178:181], v[32:35]
	s_add_u32 m0, s12, 0x5000
	v_mfma_f32_16x16x32_f16 v[16:19], v[98:101], v[178:181], v[16:19]
	global_load_lds_dwordx4 v191, s[8:9] sc1
	v_mfma_f32_16x16x32_f16 v[0:3], v[102:105], v[178:181], v[0:3]
	s_waitcnt lgkmcnt(1)
	s_add_u32 m0, s12, 0x6000
	v_mfma_f32_16x16x32_f16 v[52:55], v[106:109], v[182:185], v[52:55]
	global_load_lds_dwordx4 v192, s[8:9] sc1
	v_mfma_f32_16x16x32_f16 v[36:39], v[110:113], v[182:185], v[36:39]
	v_mfma_f32_16x16x32_f16 v[20:23], v[114:117], v[182:185], v[20:23]
	v_mfma_f32_16x16x32_f16 v[4:7], v[118:121], v[182:185], v[4:7]
	s_waitcnt lgkmcnt(0)
	s_add_u32 m0, s12, 0x7000
	v_mfma_f32_16x16x32_f16 v[48:51], v[106:109], v[186:189], v[48:51]
	global_load_lds_dwordx4 v193, s[8:9] sc1
	v_mfma_f32_16x16x32_f16 v[32:35], v[110:113], v[186:189], v[32:35]
	v_mfma_f32_16x16x32_f16 v[16:19], v[114:117], v[186:189], v[16:19]
	v_mfma_f32_16x16x32_f16 v[0:3], v[118:121], v[186:189], v[0:3]
	s_add_u32 s14, s14, 128
	s_addc_u32 s15, s15, 0
	s_add_u32 s8, s8, 128
	s_addc_u32 s9, s9, 0
	s_waitcnt vmcnt(8)
	s_barrier
	ds_read_b128 v[90:93], v194 offset:0
	ds_read_b128 v[94:97], v194 offset:2048
	ds_read_b128 v[98:101], v194 offset:4096
	ds_read_b128 v[102:105], v194 offset:6144
	ds_read_b128 v[132:135], v196 offset:24576
	ds_read_b128 v[136:139], v196 offset:26624
	ds_read_b128 v[106:109], v195 offset:0
	ds_read_b128 v[110:113], v195 offset:2048
	ds_read_b128 v[114:117], v195 offset:4096
	ds_read_b128 v[118:121], v195 offset:6144
	ds_read_b128 v[140:143], v197 offset:24576
	ds_read_b128 v[144:147], v197 offset:26624
	s_waitcnt lgkmcnt(7)
	s_add_u32 m0, s12, 0xc000
	v_mfma_f32_16x16x32_f16 v[124:127], v[90:93], v[132:135], v[124:127]
	global_load_lds_dwordx4 v190, s[10:11] sc1
	v_mfma_f32_16x16x32_f16 v[44:47], v[94:97], v[132:135], v[44:47]
	v_mfma_f32_16x16x32_f16 v[28:31], v[98:101], v[132:135], v[28:31]
	v_mfma_f32_16x16x32_f16 v[12:15], v[102:105], v[132:135], v[12:15]
	s_waitcnt lgkmcnt(6)
	s_add_u32 m0, s12, 0xd000
	v_mfma_f32_16x16x32_f16 v[56:59], v[90:93], v[136:139], v[56:59]
	global_load_lds_dwordx4 v192, s[10:11] sc1
	v_mfma_f32_16x16x32_f16 v[40:43], v[94:97], v[136:139], v[40:43]
	v_mfma_f32_16x16x32_f16 v[24:27], v[98:101], v[136:139], v[24:27]
	v_mfma_f32_16x16x32_f16 v[8:11], v[102:105], v[136:139], v[8:11]
	s_waitcnt lgkmcnt(1)
	v_mfma_f32_16x16x32_f16 v[124:127], v[106:109], v[140:143], v[124:127]
	v_mfma_f32_16x16x32_f16 v[44:47], v[110:113], v[140:143], v[44:47]
	v_mfma_f32_16x16x32_f16 v[28:31], v[114:117], v[140:143], v[28:31]
	v_mfma_f32_16x16x32_f16 v[12:15], v[118:121], v[140:143], v[12:15]
	s_waitcnt lgkmcnt(0)
	v_mfma_f32_16x16x32_f16 v[56:59], v[106:109], v[144:147], v[56:59]
	v_mfma_f32_16x16x32_f16 v[40:43], v[110:113], v[144:147], v[40:43]
	v_mfma_f32_16x16x32_f16 v[24:27], v[114:117], v[144:147], v[24:27]
	v_mfma_f32_16x16x32_f16 v[8:11], v[118:121], v[144:147], v[8:11]
	s_add_u32 s10, s10, 128
	s_addc_u32 s11, s11, 0
	s_barrier
	ds_read_b128 v[174:177], v196 offset:32768
	ds_read_b128 v[178:181], v196 offset:34816
	ds_read_b128 v[182:185], v197 offset:32768
	ds_read_b128 v[186:189], v197 offset:34816
	s_waitcnt lgkmcnt(3)
	s_add_u32 m0, s12, 0xe000
	v_mfma_f32_16x16x32_f16 v[52:55], v[90:93], v[174:177], v[52:55]
	global_load_lds_dwordx4 v190, s[14:15] sc1
	v_mfma_f32_16x16x32_f16 v[36:39], v[94:97], v[174:177], v[36:39]
	s_add_u32 m0, s12, 0xf000
	v_mfma_f32_16x16x32_f16 v[20:23], v[98:101], v[174:177], v[20:23]
	global_load_lds_dwordx4 v192, s[14:15] sc1
	v_mfma_f32_16x16x32_f16 v[4:7], v[102:105], v[174:177], v[4:7]
	s_waitcnt lgkmcnt(2)
	s_add_u32 m0, s12, 0x0
	v_mfma_f32_16x16x32_f16 v[48:51], v[90:93], v[178:181], v[48:51]
	global_load_lds_dwordx4 v190, s[8:9] sc1
	v_mfma_f32_16x16x32_f16 v[32:35], v[94:97], v[178:181], v[32:35]
	s_add_u32 m0, s12, 0x1000
	v_mfma_f32_16x16x32_f16 v[16:19], v[98:101], v[178:181], v[16:19]
	global_load_lds_dwordx4 v191, s[8:9] sc1
	v_mfma_f32_16x16x32_f16 v[0:3], v[102:105], v[178:181], v[0:3]
	s_waitcnt lgkmcnt(1)
	s_add_u32 m0, s12, 0x2000
	v_mfma_f32_16x16x32_f16 v[52:55], v[106:109], v[182:185], v[52:55]
	global_load_lds_dwordx4 v192, s[8:9] sc1
	v_mfma_f32_16x16x32_f16 v[36:39], v[110:113], v[182:185], v[36:39]
	v_mfma_f32_16x16x32_f16 v[20:23], v[114:117], v[182:185], v[20:23]
	v_mfma_f32_16x16x32_f16 v[4:7], v[118:121], v[182:185], v[4:7]
	s_waitcnt lgkmcnt(0)
	s_add_u32 m0, s12, 0x3000
	v_mfma_f32_16x16x32_f16 v[48:51], v[106:109], v[186:189], v[48:51]
	global_load_lds_dwordx4 v193, s[8:9] sc1
	v_mfma_f32_16x16x32_f16 v[32:35], v[110:113], v[186:189], v[32:35]
	v_mfma_f32_16x16x32_f16 v[16:19], v[114:117], v[186:189], v[16:19]
	v_mfma_f32_16x16x32_f16 v[0:3], v[118:121], v[186:189], v[0:3]
	s_add_u32 s14, s14, 128
	s_addc_u32 s15, s15, 0
	s_add_u32 s8, s8, 128
	s_addc_u32 s9, s9, 0
	s_waitcnt vmcnt(8)
	s_barrier
	ds_read_b128 v[90:93], v194 offset:16384
	ds_read_b128 v[94:97], v194 offset:18432
	ds_read_b128 v[98:101], v194 offset:20480
	ds_read_b128 v[102:105], v194 offset:22528
	ds_read_b128 v[132:135], v196 offset:0
	ds_read_b128 v[136:139], v196 offset:2048
	ds_read_b128 v[106:109], v195 offset:16384
	ds_read_b128 v[110:113], v195 offset:18432
	ds_read_b128 v[114:117], v195 offset:20480
	ds_read_b128 v[118:121], v195 offset:22528
	ds_read_b128 v[140:143], v197 offset:0
	ds_read_b128 v[144:147], v197 offset:2048
	s_waitcnt lgkmcnt(7)
	s_add_u32 m0, s12, 0x10000
	v_mfma_f32_16x16x32_f16 v[124:127], v[90:93], v[132:135], v[124:127]
	global_load_lds_dwordx4 v190, s[10:11] sc1
	v_mfma_f32_16x16x32_f16 v[44:47], v[94:97], v[132:135], v[44:47]
	v_mfma_f32_16x16x32_f16 v[28:31], v[98:101], v[132:135], v[28:31]
	v_mfma_f32_16x16x32_f16 v[12:15], v[102:105], v[132:135], v[12:15]
	s_waitcnt lgkmcnt(6)
	s_add_u32 m0, s12, 0x11000
	v_mfma_f32_16x16x32_f16 v[56:59], v[90:93], v[136:139], v[56:59]
	global_load_lds_dwordx4 v192, s[10:11] sc1
	v_mfma_f32_16x16x32_f16 v[40:43], v[94:97], v[136:139], v[40:43]
	v_mfma_f32_16x16x32_f16 v[24:27], v[98:101], v[136:139], v[24:27]
	v_mfma_f32_16x16x32_f16 v[8:11], v[102:105], v[136:139], v[8:11]
	s_waitcnt lgkmcnt(1)
	v_mfma_f32_16x16x32_f16 v[124:127], v[106:109], v[140:143], v[124:127]
	v_mfma_f32_16x16x32_f16 v[44:47], v[110:113], v[140:143], v[44:47]
	v_mfma_f32_16x16x32_f16 v[28:31], v[114:117], v[140:143], v[28:31]
	v_mfma_f32_16x16x32_f16 v[12:15], v[118:121], v[140:143], v[12:15]
	s_waitcnt lgkmcnt(0)
	v_mfma_f32_16x16x32_f16 v[56:59], v[106:109], v[144:147], v[56:59]
	v_mfma_f32_16x16x32_f16 v[40:43], v[110:113], v[144:147], v[40:43]
	v_mfma_f32_16x16x32_f16 v[24:27], v[114:117], v[144:147], v[24:27]
	v_mfma_f32_16x16x32_f16 v[8:11], v[118:121], v[144:147], v[8:11]
	s_add_u32 s10, s10, 128
	s_addc_u32 s11, s11, 0
	s_barrier
	ds_read_b128 v[174:177], v196 offset:8192
	ds_read_b128 v[178:181], v196 offset:10240
	ds_read_b128 v[182:185], v197 offset:8192
	ds_read_b128 v[186:189], v197 offset:10240
	s_waitcnt lgkmcnt(3)
	s_add_u32 m0, s12, 0x8000
	v_mfma_f32_16x16x32_f16 v[52:55], v[90:93], v[174:177], v[52:55]
	global_load_lds_dwordx4 v190, s[14:15] sc1
	v_mfma_f32_16x16x32_f16 v[36:39], v[94:97], v[174:177], v[36:39]
	s_add_u32 m0, s12, 0x9000
	v_mfma_f32_16x16x32_f16 v[20:23], v[98:101], v[174:177], v[20:23]
	global_load_lds_dwordx4 v192, s[14:15] sc1
	v_mfma_f32_16x16x32_f16 v[4:7], v[102:105], v[174:177], v[4:7]
	s_waitcnt lgkmcnt(2)
	s_add_u32 m0, s12, 0x4000
	v_mfma_f32_16x16x32_f16 v[48:51], v[90:93], v[178:181], v[48:51]
	global_load_lds_dwordx4 v190, s[8:9] sc1
	v_mfma_f32_16x16x32_f16 v[32:35], v[94:97], v[178:181], v[32:35]
	s_add_u32 m0, s12, 0x5000
	v_mfma_f32_16x16x32_f16 v[16:19], v[98:101], v[178:181], v[16:19]
	global_load_lds_dwordx4 v191, s[8:9] sc1
	v_mfma_f32_16x16x32_f16 v[0:3], v[102:105], v[178:181], v[0:3]
	s_waitcnt lgkmcnt(1)
	s_add_u32 m0, s12, 0x6000
	v_mfma_f32_16x16x32_f16 v[52:55], v[106:109], v[182:185], v[52:55]
	global_load_lds_dwordx4 v192, s[8:9] sc1
	v_mfma_f32_16x16x32_f16 v[36:39], v[110:113], v[182:185], v[36:39]
	v_mfma_f32_16x16x32_f16 v[20:23], v[114:117], v[182:185], v[20:23]
	v_mfma_f32_16x16x32_f16 v[4:7], v[118:121], v[182:185], v[4:7]
	s_waitcnt lgkmcnt(0)
	s_add_u32 m0, s12, 0x7000
	v_mfma_f32_16x16x32_f16 v[48:51], v[106:109], v[186:189], v[48:51]
	global_load_lds_dwordx4 v193, s[8:9] sc1
	v_mfma_f32_16x16x32_f16 v[32:35], v[110:113], v[186:189], v[32:35]
	v_mfma_f32_16x16x32_f16 v[16:19], v[114:117], v[186:189], v[16:19]
	v_mfma_f32_16x16x32_f16 v[0:3], v[118:121], v[186:189], v[0:3]
	s_add_u32 s14, s14, 128
	s_addc_u32 s15, s15, 0
	s_add_u32 s8, s8, 128
	s_addc_u32 s9, s9, 0
	s_waitcnt vmcnt(8)
	s_barrier
	ds_read_b128 v[90:93], v194 offset:0
	ds_read_b128 v[94:97], v194 offset:2048
	ds_read_b128 v[98:101], v194 offset:4096
	ds_read_b128 v[102:105], v194 offset:6144
	ds_read_b128 v[132:135], v196 offset:16384
	ds_read_b128 v[136:139], v196 offset:18432
	ds_read_b128 v[106:109], v195 offset:0
	ds_read_b128 v[110:113], v195 offset:2048
	ds_read_b128 v[114:117], v195 offset:4096
	ds_read_b128 v[118:121], v195 offset:6144
	ds_read_b128 v[140:143], v197 offset:16384
	ds_read_b128 v[144:147], v197 offset:18432
	s_waitcnt lgkmcnt(7)
	s_add_u32 m0, s12, 0xa000
	v_mfma_f32_16x16x32_f16 v[124:127], v[90:93], v[132:135], v[124:127]
	global_load_lds_dwordx4 v190, s[10:11] sc1
	v_mfma_f32_16x16x32_f16 v[44:47], v[94:97], v[132:135], v[44:47]
	v_mfma_f32_16x16x32_f16 v[28:31], v[98:101], v[132:135], v[28:31]
	v_mfma_f32_16x16x32_f16 v[12:15], v[102:105], v[132:135], v[12:15]
	s_waitcnt lgkmcnt(6)
	s_add_u32 m0, s12, 0xb000
	v_mfma_f32_16x16x32_f16 v[56:59], v[90:93], v[136:139], v[56:59]
	global_load_lds_dwordx4 v192, s[10:11] sc1
	v_mfma_f32_16x16x32_f16 v[40:43], v[94:97], v[136:139], v[40:43]
	v_mfma_f32_16x16x32_f16 v[24:27], v[98:101], v[136:139], v[24:27]
	v_mfma_f32_16x16x32_f16 v[8:11], v[102:105], v[136:139], v[8:11]
	s_waitcnt lgkmcnt(1)
	v_mfma_f32_16x16x32_f16 v[124:127], v[106:109], v[140:143], v[124:127]
	v_mfma_f32_16x16x32_f16 v[44:47], v[110:113], v[140:143], v[44:47]
	v_mfma_f32_16x16x32_f16 v[28:31], v[114:117], v[140:143], v[28:31]
	v_mfma_f32_16x16x32_f16 v[12:15], v[118:121], v[140:143], v[12:15]
	s_waitcnt lgkmcnt(0)
	v_mfma_f32_16x16x32_f16 v[56:59], v[106:109], v[144:147], v[56:59]
	v_mfma_f32_16x16x32_f16 v[40:43], v[110:113], v[144:147], v[40:43]
	v_mfma_f32_16x16x32_f16 v[24:27], v[114:117], v[144:147], v[24:27]
	v_mfma_f32_16x16x32_f16 v[8:11], v[118:121], v[144:147], v[8:11]
	s_add_u32 s10, s10, 128
	s_addc_u32 s11, s11, 0
	s_barrier
	ds_read_b128 v[174:177], v196 offset:24576
	ds_read_b128 v[178:181], v196 offset:26624
	ds_read_b128 v[182:185], v197 offset:24576
	ds_read_b128 v[186:189], v197 offset:26624
	s_waitcnt lgkmcnt(3)
	s_add_u32 m0, s12, 0xc000
	v_mfma_f32_16x16x32_f16 v[52:55], v[90:93], v[174:177], v[52:55]
	global_load_lds_dwordx4 v190, s[14:15] sc1
	v_mfma_f32_16x16x32_f16 v[36:39], v[94:97], v[174:177], v[36:39]
	s_add_u32 m0, s12, 0xd000
	v_mfma_f32_16x16x32_f16 v[20:23], v[98:101], v[174:177], v[20:23]
	global_load_lds_dwordx4 v192, s[14:15] sc1
	v_mfma_f32_16x16x32_f16 v[4:7], v[102:105], v[174:177], v[4:7]
	s_waitcnt lgkmcnt(2)
	s_add_u32 m0, s12, 0x0
	v_mfma_f32_16x16x32_f16 v[48:51], v[90:93], v[178:181], v[48:51]
	global_load_lds_dwordx4 v190, s[8:9] sc1
	v_mfma_f32_16x16x32_f16 v[32:35], v[94:97], v[178:181], v[32:35]
	s_add_u32 m0, s12, 0x1000
	v_mfma_f32_16x16x32_f16 v[16:19], v[98:101], v[178:181], v[16:19]
	global_load_lds_dwordx4 v191, s[8:9] sc1
	v_mfma_f32_16x16x32_f16 v[0:3], v[102:105], v[178:181], v[0:3]
	s_waitcnt lgkmcnt(1)
	s_add_u32 m0, s12, 0x2000
	v_mfma_f32_16x16x32_f16 v[52:55], v[106:109], v[182:185], v[52:55]
	global_load_lds_dwordx4 v192, s[8:9] sc1
	v_mfma_f32_16x16x32_f16 v[36:39], v[110:113], v[182:185], v[36:39]
	v_mfma_f32_16x16x32_f16 v[20:23], v[114:117], v[182:185], v[20:23]
	v_mfma_f32_16x16x32_f16 v[4:7], v[118:121], v[182:185], v[4:7]
	s_waitcnt lgkmcnt(0)
	s_add_u32 m0, s12, 0x3000
	v_mfma_f32_16x16x32_f16 v[48:51], v[106:109], v[186:189], v[48:51]
	global_load_lds_dwordx4 v193, s[8:9] sc1
	v_mfma_f32_16x16x32_f16 v[32:35], v[110:113], v[186:189], v[32:35]
	v_mfma_f32_16x16x32_f16 v[16:19], v[114:117], v[186:189], v[16:19]
	v_mfma_f32_16x16x32_f16 v[0:3], v[118:121], v[186:189], v[0:3]
	s_add_u32 s14, s14, 128
	s_addc_u32 s15, s15, 0
	s_add_u32 s8, s8, 128
	s_addc_u32 s9, s9, 0
	s_waitcnt vmcnt(8)
	s_barrier
	ds_read_b128 v[90:93], v194 offset:16384
	ds_read_b128 v[94:97], v194 offset:18432
	ds_read_b128 v[98:101], v194 offset:20480
	ds_read_b128 v[102:105], v194 offset:22528
	ds_read_b128 v[132:135], v196 offset:32768
	ds_read_b128 v[136:139], v196 offset:34816
	ds_read_b128 v[106:109], v195 offset:16384
	ds_read_b128 v[110:113], v195 offset:18432
	ds_read_b128 v[114:117], v195 offset:20480
	ds_read_b128 v[118:121], v195 offset:22528
	ds_read_b128 v[140:143], v197 offset:32768
	ds_read_b128 v[144:147], v197 offset:34816
	s_waitcnt lgkmcnt(7)
	s_add_u32 m0, s12, 0xe000
	v_mfma_f32_16x16x32_f16 v[124:127], v[90:93], v[132:135], v[124:127]
	global_load_lds_dwordx4 v190, s[10:11] sc1
	v_mfma_f32_16x16x32_f16 v[44:47], v[94:97], v[132:135], v[44:47]
	v_mfma_f32_16x16x32_f16 v[28:31], v[98:101], v[132:135], v[28:31]
	v_mfma_f32_16x16x32_f16 v[12:15], v[102:105], v[132:135], v[12:15]
	s_waitcnt lgkmcnt(6)
	s_add_u32 m0, s12, 0xf000
	v_mfma_f32_16x16x32_f16 v[56:59], v[90:93], v[136:139], v[56:59]
	global_load_lds_dwordx4 v192, s[10:11] sc1
	v_mfma_f32_16x16x32_f16 v[40:43], v[94:97], v[136:139], v[40:43]
	v_mfma_f32_16x16x32_f16 v[24:27], v[98:101], v[136:139], v[24:27]
	v_mfma_f32_16x16x32_f16 v[8:11], v[102:105], v[136:139], v[8:11]
	s_waitcnt lgkmcnt(1)
	v_mfma_f32_16x16x32_f16 v[124:127], v[106:109], v[140:143], v[124:127]
	v_mfma_f32_16x16x32_f16 v[44:47], v[110:113], v[140:143], v[44:47]
	v_mfma_f32_16x16x32_f16 v[28:31], v[114:117], v[140:143], v[28:31]
	v_mfma_f32_16x16x32_f16 v[12:15], v[118:121], v[140:143], v[12:15]
	s_waitcnt lgkmcnt(0)
	v_mfma_f32_16x16x32_f16 v[56:59], v[106:109], v[144:147], v[56:59]
	v_mfma_f32_16x16x32_f16 v[40:43], v[110:113], v[144:147], v[40:43]
	v_mfma_f32_16x16x32_f16 v[24:27], v[114:117], v[144:147], v[24:27]
	v_mfma_f32_16x16x32_f16 v[8:11], v[118:121], v[144:147], v[8:11]
	s_add_u32 s10, s10, 128
	s_addc_u32 s11, s11, 0
	s_barrier
	ds_read_b128 v[174:177], v196 offset:0
	ds_read_b128 v[178:181], v196 offset:2048
	ds_read_b128 v[182:185], v197 offset:0
	ds_read_b128 v[186:189], v197 offset:2048
	s_waitcnt lgkmcnt(3)
	s_add_u32 m0, s12, 0x10000
	v_mfma_f32_16x16x32_f16 v[52:55], v[90:93], v[174:177], v[52:55]
	global_load_lds_dwordx4 v190, s[14:15] sc1
	v_mfma_f32_16x16x32_f16 v[36:39], v[94:97], v[174:177], v[36:39]
	s_add_u32 m0, s12, 0x11000
	v_mfma_f32_16x16x32_f16 v[20:23], v[98:101], v[174:177], v[20:23]
	global_load_lds_dwordx4 v192, s[14:15] sc1
	v_mfma_f32_16x16x32_f16 v[4:7], v[102:105], v[174:177], v[4:7]
	s_waitcnt lgkmcnt(2)
	s_add_u32 m0, s12, 0x4000
	v_mfma_f32_16x16x32_f16 v[48:51], v[90:93], v[178:181], v[48:51]
	global_load_lds_dwordx4 v190, s[8:9] sc1
	v_mfma_f32_16x16x32_f16 v[32:35], v[94:97], v[178:181], v[32:35]
	s_add_u32 m0, s12, 0x5000
	v_mfma_f32_16x16x32_f16 v[16:19], v[98:101], v[178:181], v[16:19]
	global_load_lds_dwordx4 v191, s[8:9] sc1
	v_mfma_f32_16x16x32_f16 v[0:3], v[102:105], v[178:181], v[0:3]
	s_waitcnt lgkmcnt(1)
	s_add_u32 m0, s12, 0x6000
	v_mfma_f32_16x16x32_f16 v[52:55], v[106:109], v[182:185], v[52:55]
	global_load_lds_dwordx4 v192, s[8:9] sc1
	v_mfma_f32_16x16x32_f16 v[36:39], v[110:113], v[182:185], v[36:39]
	v_mfma_f32_16x16x32_f16 v[20:23], v[114:117], v[182:185], v[20:23]
	v_mfma_f32_16x16x32_f16 v[4:7], v[118:121], v[182:185], v[4:7]
	s_waitcnt lgkmcnt(0)
	s_add_u32 m0, s12, 0x7000
	v_mfma_f32_16x16x32_f16 v[48:51], v[106:109], v[186:189], v[48:51]
	global_load_lds_dwordx4 v193, s[8:9] sc1
	v_mfma_f32_16x16x32_f16 v[32:35], v[110:113], v[186:189], v[32:35]
	v_mfma_f32_16x16x32_f16 v[16:19], v[114:117], v[186:189], v[16:19]
	v_mfma_f32_16x16x32_f16 v[0:3], v[118:121], v[186:189], v[0:3]
	s_add_u32 s14, s14, 128
	s_addc_u32 s15, s15, 0
	s_add_u32 s8, s8, 128
	s_addc_u32 s9, s9, 0
	s_waitcnt vmcnt(8)
	s_barrier
	ds_read_b128 v[90:93], v194 offset:0
	ds_read_b128 v[94:97], v194 offset:2048
	ds_read_b128 v[98:101], v194 offset:4096
	ds_read_b128 v[102:105], v194 offset:6144
	ds_read_b128 v[132:135], v196 offset:8192
	ds_read_b128 v[136:139], v196 offset:10240
	ds_read_b128 v[106:109], v195 offset:0
	ds_read_b128 v[110:113], v195 offset:2048
	ds_read_b128 v[114:117], v195 offset:4096
	ds_read_b128 v[118:121], v195 offset:6144
	ds_read_b128 v[140:143], v197 offset:8192
	ds_read_b128 v[144:147], v197 offset:10240
	s_waitcnt lgkmcnt(7)
	s_add_u32 m0, s12, 0x8000
	v_mfma_f32_16x16x32_f16 v[124:127], v[90:93], v[132:135], v[124:127]
	global_load_lds_dwordx4 v190, s[10:11] sc1
	v_mfma_f32_16x16x32_f16 v[44:47], v[94:97], v[132:135], v[44:47]
	v_mfma_f32_16x16x32_f16 v[28:31], v[98:101], v[132:135], v[28:31]
	v_mfma_f32_16x16x32_f16 v[12:15], v[102:105], v[132:135], v[12:15]
	s_waitcnt lgkmcnt(6)
	s_add_u32 m0, s12, 0x9000
	v_mfma_f32_16x16x32_f16 v[56:59], v[90:93], v[136:139], v[56:59]
	global_load_lds_dwordx4 v192, s[10:11] sc1
	v_mfma_f32_16x16x32_f16 v[40:43], v[94:97], v[136:139], v[40:43]
	v_mfma_f32_16x16x32_f16 v[24:27], v[98:101], v[136:139], v[24:27]
	v_mfma_f32_16x16x32_f16 v[8:11], v[102:105], v[136:139], v[8:11]
	s_waitcnt lgkmcnt(1)
	v_mfma_f32_16x16x32_f16 v[124:127], v[106:109], v[140:143], v[124:127]
	v_mfma_f32_16x16x32_f16 v[44:47], v[110:113], v[140:143], v[44:47]
	v_mfma_f32_16x16x32_f16 v[28:31], v[114:117], v[140:143], v[28:31]
	v_mfma_f32_16x16x32_f16 v[12:15], v[118:121], v[140:143], v[12:15]
	s_waitcnt lgkmcnt(0)
	v_mfma_f32_16x16x32_f16 v[56:59], v[106:109], v[144:147], v[56:59]
	v_mfma_f32_16x16x32_f16 v[40:43], v[110:113], v[144:147], v[40:43]
	v_mfma_f32_16x16x32_f16 v[24:27], v[114:117], v[144:147], v[24:27]
	v_mfma_f32_16x16x32_f16 v[8:11], v[118:121], v[144:147], v[8:11]
	s_add_u32 s10, s10, 128
	s_addc_u32 s11, s11, 0
	s_barrier
	ds_read_b128 v[174:177], v196 offset:16384
	ds_read_b128 v[178:181], v196 offset:18432
	ds_read_b128 v[182:185], v197 offset:16384
	ds_read_b128 v[186:189], v197 offset:18432
	s_waitcnt lgkmcnt(3)
	s_add_u32 m0, s12, 0xa000
	v_mfma_f32_16x16x32_f16 v[52:55], v[90:93], v[174:177], v[52:55]
	global_load_lds_dwordx4 v190, s[14:15] sc1
	v_mfma_f32_16x16x32_f16 v[36:39], v[94:97], v[174:177], v[36:39]
	s_add_u32 m0, s12, 0xb000
	v_mfma_f32_16x16x32_f16 v[20:23], v[98:101], v[174:177], v[20:23]
	global_load_lds_dwordx4 v192, s[14:15] sc1
	v_mfma_f32_16x16x32_f16 v[4:7], v[102:105], v[174:177], v[4:7]
	s_waitcnt lgkmcnt(2)
	s_add_u32 m0, s12, 0x0
	v_mfma_f32_16x16x32_f16 v[48:51], v[90:93], v[178:181], v[48:51]
	global_load_lds_dwordx4 v190, s[8:9] sc1
	v_mfma_f32_16x16x32_f16 v[32:35], v[94:97], v[178:181], v[32:35]
	s_add_u32 m0, s12, 0x1000
	v_mfma_f32_16x16x32_f16 v[16:19], v[98:101], v[178:181], v[16:19]
	global_load_lds_dwordx4 v191, s[8:9] sc1
	v_mfma_f32_16x16x32_f16 v[0:3], v[102:105], v[178:181], v[0:3]
	s_waitcnt lgkmcnt(1)
	s_add_u32 m0, s12, 0x2000
	v_mfma_f32_16x16x32_f16 v[52:55], v[106:109], v[182:185], v[52:55]
	global_load_lds_dwordx4 v192, s[8:9] sc1
	v_mfma_f32_16x16x32_f16 v[36:39], v[110:113], v[182:185], v[36:39]
	v_mfma_f32_16x16x32_f16 v[20:23], v[114:117], v[182:185], v[20:23]
	v_mfma_f32_16x16x32_f16 v[4:7], v[118:121], v[182:185], v[4:7]
	s_waitcnt lgkmcnt(0)
	s_add_u32 m0, s12, 0x3000
	v_mfma_f32_16x16x32_f16 v[48:51], v[106:109], v[186:189], v[48:51]
	global_load_lds_dwordx4 v193, s[8:9] sc1
	v_mfma_f32_16x16x32_f16 v[32:35], v[110:113], v[186:189], v[32:35]
	v_mfma_f32_16x16x32_f16 v[16:19], v[114:117], v[186:189], v[16:19]
	v_mfma_f32_16x16x32_f16 v[0:3], v[118:121], v[186:189], v[0:3]
	s_add_u32 s14, s14, 128
	s_addc_u32 s15, s15, 0
	s_add_u32 s8, s8, 128
	s_addc_u32 s9, s9, 0
	s_waitcnt vmcnt(8)
	s_barrier
	ds_read_b128 v[90:93], v194 offset:16384
	ds_read_b128 v[94:97], v194 offset:18432
	ds_read_b128 v[98:101], v194 offset:20480
	ds_read_b128 v[102:105], v194 offset:22528
	ds_read_b128 v[132:135], v196 offset:24576
	ds_read_b128 v[136:139], v196 offset:26624
	ds_read_b128 v[106:109], v195 offset:16384
	ds_read_b128 v[110:113], v195 offset:18432
	ds_read_b128 v[114:117], v195 offset:20480
	ds_read_b128 v[118:121], v195 offset:22528
	ds_read_b128 v[140:143], v197 offset:24576
	ds_read_b128 v[144:147], v197 offset:26624
	s_waitcnt lgkmcnt(7)
	s_add_u32 m0, s12, 0xc000
	v_mfma_f32_16x16x32_f16 v[124:127], v[90:93], v[132:135], v[124:127]
	global_load_lds_dwordx4 v190, s[10:11] sc1
	v_mfma_f32_16x16x32_f16 v[44:47], v[94:97], v[132:135], v[44:47]
	v_mfma_f32_16x16x32_f16 v[28:31], v[98:101], v[132:135], v[28:31]
	v_mfma_f32_16x16x32_f16 v[12:15], v[102:105], v[132:135], v[12:15]
	s_waitcnt lgkmcnt(6)
	s_add_u32 m0, s12, 0xd000
	v_mfma_f32_16x16x32_f16 v[56:59], v[90:93], v[136:139], v[56:59]
	global_load_lds_dwordx4 v192, s[10:11] sc1
	v_mfma_f32_16x16x32_f16 v[40:43], v[94:97], v[136:139], v[40:43]
	v_mfma_f32_16x16x32_f16 v[24:27], v[98:101], v[136:139], v[24:27]
	v_mfma_f32_16x16x32_f16 v[8:11], v[102:105], v[136:139], v[8:11]
	s_waitcnt lgkmcnt(1)
	v_mfma_f32_16x16x32_f16 v[124:127], v[106:109], v[140:143], v[124:127]
	v_mfma_f32_16x16x32_f16 v[44:47], v[110:113], v[140:143], v[44:47]
	v_mfma_f32_16x16x32_f16 v[28:31], v[114:117], v[140:143], v[28:31]
	v_mfma_f32_16x16x32_f16 v[12:15], v[118:121], v[140:143], v[12:15]
	s_waitcnt lgkmcnt(0)
	v_mfma_f32_16x16x32_f16 v[56:59], v[106:109], v[144:147], v[56:59]
	v_mfma_f32_16x16x32_f16 v[40:43], v[110:113], v[144:147], v[40:43]
	v_mfma_f32_16x16x32_f16 v[24:27], v[114:117], v[144:147], v[24:27]
	v_mfma_f32_16x16x32_f16 v[8:11], v[118:121], v[144:147], v[8:11]
	s_add_u32 s10, s10, 128
	s_addc_u32 s11, s11, 0
	s_barrier
	ds_read_b128 v[174:177], v196 offset:32768
	ds_read_b128 v[178:181], v196 offset:34816
	ds_read_b128 v[182:185], v197 offset:32768
	ds_read_b128 v[186:189], v197 offset:34816
	s_waitcnt lgkmcnt(3)
	s_add_u32 m0, s12, 0xe000
	v_mfma_f32_16x16x32_f16 v[52:55], v[90:93], v[174:177], v[52:55]
	global_load_lds_dwordx4 v190, s[14:15] sc1
	v_mfma_f32_16x16x32_f16 v[36:39], v[94:97], v[174:177], v[36:39]
	s_add_u32 m0, s12, 0xf000
	v_mfma_f32_16x16x32_f16 v[20:23], v[98:101], v[174:177], v[20:23]
	global_load_lds_dwordx4 v192, s[14:15] sc1
	v_mfma_f32_16x16x32_f16 v[4:7], v[102:105], v[174:177], v[4:7]
	s_waitcnt lgkmcnt(2)
	s_add_u32 m0, s12, 0x4000
	v_mfma_f32_16x16x32_f16 v[48:51], v[90:93], v[178:181], v[48:51]
	global_load_lds_dwordx4 v190, s[8:9] sc1
	v_mfma_f32_16x16x32_f16 v[32:35], v[94:97], v[178:181], v[32:35]
	s_add_u32 m0, s12, 0x5000
	v_mfma_f32_16x16x32_f16 v[16:19], v[98:101], v[178:181], v[16:19]
	global_load_lds_dwordx4 v191, s[8:9] sc1
	v_mfma_f32_16x16x32_f16 v[0:3], v[102:105], v[178:181], v[0:3]
	s_waitcnt lgkmcnt(1)
	s_add_u32 m0, s12, 0x6000
	v_mfma_f32_16x16x32_f16 v[52:55], v[106:109], v[182:185], v[52:55]
	global_load_lds_dwordx4 v192, s[8:9] sc1
	v_mfma_f32_16x16x32_f16 v[36:39], v[110:113], v[182:185], v[36:39]
	v_mfma_f32_16x16x32_f16 v[20:23], v[114:117], v[182:185], v[20:23]
	v_mfma_f32_16x16x32_f16 v[4:7], v[118:121], v[182:185], v[4:7]
	s_waitcnt lgkmcnt(0)
	s_add_u32 m0, s12, 0x7000
	v_mfma_f32_16x16x32_f16 v[48:51], v[106:109], v[186:189], v[48:51]
	global_load_lds_dwordx4 v193, s[8:9] sc1
	v_mfma_f32_16x16x32_f16 v[32:35], v[110:113], v[186:189], v[32:35]
	v_mfma_f32_16x16x32_f16 v[16:19], v[114:117], v[186:189], v[16:19]
	v_mfma_f32_16x16x32_f16 v[0:3], v[118:121], v[186:189], v[0:3]
	s_add_u32 s14, s14, 128
	s_addc_u32 s15, s15, 0
	s_add_u32 s8, s8, 128
	s_addc_u32 s9, s9, 0
	s_add_i32 s13, s13, 1
	s_cmp_lt_u32 s13, 3
	s_cbranch_scc1 .Lgout_loop
	global_load_dwordx4 v[60:63], v148, s[38:39] offset:0
	global_load_dwordx4 v[64:67], v148, s[38:39] offset:64
	global_load_dwordx4 v[68:71], v148, s[38:39] offset:128
	global_load_dwordx4 v[72:75], v148, s[38:39] offset:192
	global_load_dwordx4 v[76:79], v150, s[36:37] offset:0
	global_load_dwordx4 v[80:83], v150, s[36:37] offset:64
	global_load_dwordx4 v[84:87], v150, s[36:37] offset:128
	global_load_dwordx4 v[200:203], v150, s[36:37] offset:192
	global_load_dwordx4 v[204:207], v151, s[36:37] offset:0
	global_load_dwordx4 v[210:213], v151, s[36:37] offset:64
	global_load_dwordx4 v[222:225], v151, s[36:37] offset:128
	global_load_dwordx4 v[226:229], v151, s[36:37] offset:192
	global_load_dwordx4 v[230:233], v152, s[36:37] offset:0
	global_load_dwordx4 v[234:237], v152, s[36:37] offset:64
	global_load_dwordx4 v[238:241], v152, s[36:37] offset:128
	global_load_dwordx4 v[242:245], v152, s[36:37] offset:192
	global_load_dwordx4 v[246:249], v153, s[36:37] offset:0
	global_load_dwordx4 v[158:161], v153, s[36:37] offset:64
	global_load_dwordx4 v[162:165], v153, s[36:37] offset:128
	global_load_dwordx4 v[154:157], v153, s[36:37] offset:192
	s_waitcnt vmcnt(28)
	s_barrier
	ds_read_b128 v[90:93], v194 offset:0
	ds_read_b128 v[94:97], v194 offset:2048
	ds_read_b128 v[98:101], v194 offset:4096
	ds_read_b128 v[102:105], v194 offset:6144
	ds_read_b128 v[132:135], v196 offset:0
	ds_read_b128 v[136:139], v196 offset:2048
	ds_read_b128 v[106:109], v195 offset:0
	ds_read_b128 v[110:113], v195 offset:2048
	ds_read_b128 v[114:117], v195 offset:4096
	ds_read_b128 v[118:121], v195 offset:6144
	ds_read_b128 v[140:143], v197 offset:0
	ds_read_b128 v[144:147], v197 offset:2048
	s_waitcnt lgkmcnt(7)
	v_mfma_f32_16x16x32_f16 v[124:127], v[90:93], v[132:135], v[124:127]
	v_mfma_f32_16x16x32_f16 v[44:47], v[94:97], v[132:135], v[44:47]
	v_mfma_f32_16x16x32_f16 v[28:31], v[98:101], v[132:135], v[28:31]
	v_mfma_f32_16x16x32_f16 v[12:15], v[102:105], v[132:135], v[12:15]
	s_waitcnt lgkmcnt(6)
	v_mfma_f32_16x16x32_f16 v[56:59], v[90:93], v[136:139], v[56:59]
	v_mfma_f32_16x16x32_f16 v[40:43], v[94:97], v[136:139], v[40:43]
	v_mfma_f32_16x16x32_f16 v[24:27], v[98:101], v[136:139], v[24:27]
	v_mfma_f32_16x16x32_f16 v[8:11], v[102:105], v[136:139], v[8:11]
	s_waitcnt lgkmcnt(1)
	v_mfma_f32_16x16x32_f16 v[124:127], v[106:109], v[140:143], v[124:127]
	v_mfma_f32_16x16x32_f16 v[44:47], v[110:113], v[140:143], v[44:47]
	v_mfma_f32_16x16x32_f16 v[28:31], v[114:117], v[140:143], v[28:31]
	v_mfma_f32_16x16x32_f16 v[12:15], v[118:121], v[140:143], v[12:15]
	s_waitcnt lgkmcnt(0)
	v_mfma_f32_16x16x32_f16 v[56:59], v[106:109], v[144:147], v[56:59]
	v_mfma_f32_16x16x32_f16 v[40:43], v[110:113], v[144:147], v[40:43]
	v_mfma_f32_16x16x32_f16 v[24:27], v[114:117], v[144:147], v[24:27]
	v_mfma_f32_16x16x32_f16 v[8:11], v[118:121], v[144:147], v[8:11]
	s_barrier
	ds_read_b128 v[174:177], v196 offset:8192
	ds_read_b128 v[178:181], v196 offset:10240
	ds_read_b128 v[182:185], v197 offset:8192
	ds_read_b128 v[186:189], v197 offset:10240
	s_waitcnt lgkmcnt(3)
	v_mfma_f32_16x16x32_f16 v[52:55], v[90:93], v[174:177], v[52:55]
	v_mfma_f32_16x16x32_f16 v[36:39], v[94:97], v[174:177], v[36:39]
	v_mfma_f32_16x16x32_f16 v[20:23], v[98:101], v[174:177], v[20:23]
	v_mfma_f32_16x16x32_f16 v[4:7], v[102:105], v[174:177], v[4:7]
	s_waitcnt lgkmcnt(2)
	v_mfma_f32_16x16x32_f16 v[48:51], v[90:93], v[178:181], v[48:51]
	v_mfma_f32_16x16x32_f16 v[32:35], v[94:97], v[178:181], v[32:35]
	v_mfma_f32_16x16x32_f16 v[16:19], v[98:101], v[178:181], v[16:19]
	v_mfma_f32_16x16x32_f16 v[0:3], v[102:105], v[178:181], v[0:3]
	s_waitcnt lgkmcnt(1)
	v_mfma_f32_16x16x32_f16 v[52:55], v[106:109], v[182:185], v[52:55]
	v_mfma_f32_16x16x32_f16 v[36:39], v[110:113], v[182:185], v[36:39]
	v_mfma_f32_16x16x32_f16 v[20:23], v[114:117], v[182:185], v[20:23]
	v_mfma_f32_16x16x32_f16 v[4:7], v[118:121], v[182:185], v[4:7]
	s_waitcnt lgkmcnt(0)
	v_mfma_f32_16x16x32_f16 v[48:51], v[106:109], v[186:189], v[48:51]
	v_mfma_f32_16x16x32_f16 v[32:35], v[110:113], v[186:189], v[32:35]
	v_mfma_f32_16x16x32_f16 v[16:19], v[114:117], v[186:189], v[16:19]
	v_mfma_f32_16x16x32_f16 v[0:3], v[118:121], v[186:189], v[0:3]
	s_waitcnt vmcnt(20)
	s_barrier
	ds_read_b128 v[90:93], v194 offset:16384
	ds_read_b128 v[94:97], v194 offset:18432
	ds_read_b128 v[98:101], v194 offset:20480
	ds_read_b128 v[102:105], v194 offset:22528
	ds_read_b128 v[132:135], v196 offset:16384
	ds_read_b128 v[136:139], v196 offset:18432
	ds_read_b128 v[106:109], v195 offset:16384
	ds_read_b128 v[110:113], v195 offset:18432
	ds_read_b128 v[114:117], v195 offset:20480
	ds_read_b128 v[118:121], v195 offset:22528
	ds_read_b128 v[140:143], v197 offset:16384
	ds_read_b128 v[144:147], v197 offset:18432
	s_waitcnt lgkmcnt(7)
	v_mfma_f32_16x16x32_f16 v[124:127], v[90:93], v[132:135], v[124:127]
	v_mfma_f32_16x16x32_f16 v[44:47], v[94:97], v[132:135], v[44:47]
	v_mfma_f32_16x16x32_f16 v[28:31], v[98:101], v[132:135], v[28:31]
	v_mfma_f32_16x16x32_f16 v[12:15], v[102:105], v[132:135], v[12:15]
	s_waitcnt lgkmcnt(6)
	v_mfma_f32_16x16x32_f16 v[56:59], v[90:93], v[136:139], v[56:59]
	v_mfma_f32_16x16x32_f16 v[40:43], v[94:97], v[136:139], v[40:43]
	v_mfma_f32_16x16x32_f16 v[24:27], v[98:101], v[136:139], v[24:27]
	v_mfma_f32_16x16x32_f16 v[8:11], v[102:105], v[136:139], v[8:11]
	s_waitcnt lgkmcnt(1)
	v_mfma_f32_16x16x32_f16 v[124:127], v[106:109], v[140:143], v[124:127]
	v_mfma_f32_16x16x32_f16 v[44:47], v[110:113], v[140:143], v[44:47]
	v_mfma_f32_16x16x32_f16 v[28:31], v[114:117], v[140:143], v[28:31]
	v_mfma_f32_16x16x32_f16 v[12:15], v[118:121], v[140:143], v[12:15]
	s_waitcnt lgkmcnt(0)
	v_mfma_f32_16x16x32_f16 v[56:59], v[106:109], v[144:147], v[56:59]
	v_mfma_f32_16x16x32_f16 v[40:43], v[110:113], v[144:147], v[40:43]
	v_mfma_f32_16x16x32_f16 v[24:27], v[114:117], v[144:147], v[24:27]
	v_mfma_f32_16x16x32_f16 v[8:11], v[118:121], v[144:147], v[8:11]
	s_barrier
	ds_read_b128 v[174:177], v196 offset:24576
	ds_read_b128 v[178:181], v196 offset:26624
	ds_read_b128 v[182:185], v197 offset:24576
	ds_read_b128 v[186:189], v197 offset:26624
	s_waitcnt lgkmcnt(3)
	v_mfma_f32_16x16x32_f16 v[52:55], v[90:93], v[174:177], v[52:55]
	v_mfma_f32_16x16x32_f16 v[36:39], v[94:97], v[174:177], v[36:39]
	v_mfma_f32_16x16x32_f16 v[20:23], v[98:101], v[174:177], v[20:23]
	v_mfma_f32_16x16x32_f16 v[4:7], v[102:105], v[174:177], v[4:7]
	s_waitcnt lgkmcnt(2)
	v_mfma_f32_16x16x32_f16 v[48:51], v[90:93], v[178:181], v[48:51]
	v_mfma_f32_16x16x32_f16 v[32:35], v[94:97], v[178:181], v[32:35]
	v_mfma_f32_16x16x32_f16 v[16:19], v[98:101], v[178:181], v[16:19]
	v_mfma_f32_16x16x32_f16 v[0:3], v[102:105], v[178:181], v[0:3]
	s_waitcnt lgkmcnt(1)
	v_mfma_f32_16x16x32_f16 v[52:55], v[106:109], v[182:185], v[52:55]
	v_mfma_f32_16x16x32_f16 v[36:39], v[110:113], v[182:185], v[36:39]
	v_mfma_f32_16x16x32_f16 v[20:23], v[114:117], v[182:185], v[20:23]
	v_mfma_f32_16x16x32_f16 v[4:7], v[118:121], v[182:185], v[4:7]
	s_waitcnt lgkmcnt(0)
	v_mfma_f32_16x16x32_f16 v[48:51], v[106:109], v[186:189], v[48:51]
	v_mfma_f32_16x16x32_f16 v[32:35], v[110:113], v[186:189], v[32:35]
	v_mfma_f32_16x16x32_f16 v[16:19], v[114:117], v[186:189], v[16:19]
	v_mfma_f32_16x16x32_f16 v[0:3], v[118:121], v[186:189], v[0:3]
	s_nop 7
	s_waitcnt vmcnt(0)
	v_pk_mul_f32 v[124:125], v[124:125], v[60:61]
	v_pk_mul_f32 v[126:127], v[126:127], v[62:63]
	v_pk_fma_f32 v[124:125], v[76:77], s[96:97], v[124:125] op_sel_hi:[1,0,1]
	v_pk_fma_f32 v[126:127], v[78:79], s[96:97], v[126:127] op_sel_hi:[1,0,1]
	global_store_dwordx4 v150, v[124:127], s[18:19] offset:0
	v_pk_mul_f32 v[44:45], v[44:45], v[64:65]
	v_pk_mul_f32 v[46:47], v[46:47], v[66:67]
	v_pk_fma_f32 v[44:45], v[80:81], s[96:97], v[44:45] op_sel_hi:[1,0,1]
	v_pk_fma_f32 v[46:47], v[82:83], s[96:97], v[46:47] op_sel_hi:[1,0,1]
	global_store_dwordx4 v150, v[44:47], s[18:19] offset:64
	v_pk_mul_f32 v[28:29], v[28:29], v[68:69]
	v_pk_mul_f32 v[30:31], v[30:31], v[70:71]
	v_pk_fma_f32 v[28:29], v[84:85], s[96:97], v[28:29] op_sel_hi:[1,0,1]
	v_pk_fma_f32 v[30:31], v[86:87], s[96:97], v[30:31] op_sel_hi:[1,0,1]
	global_store_dwordx4 v150, v[28:31], s[18:19] offset:128
	v_pk_mul_f32 v[12:13], v[12:13], v[72:73]
	v_pk_mul_f32 v[14:15], v[14:15], v[74:75]
	v_pk_fma_f32 v[12:13], v[200:201], s[96:97], v[12:13] op_sel_hi:[1,0,1]
	v_pk_fma_f32 v[14:15], v[202:203], s[96:97], v[14:15] op_sel_hi:[1,0,1]
	global_store_dwordx4 v150, v[12:15], s[18:19] offset:192
	v_pk_mul_f32 v[56:57], v[56:57], v[60:61]
	v_pk_mul_f32 v[58:59], v[58:59], v[62:63]
	v_pk_fma_f32 v[56:57], v[204:205], s[96:97], v[56:57] op_sel_hi:[1,0,1]
	v_pk_fma_f32 v[58:59], v[206:207], s[96:97], v[58:59] op_sel_hi:[1,0,1]
	global_store_dwordx4 v151, v[56:59], s[18:19] offset:0
	v_pk_mul_f32 v[40:41], v[40:41], v[64:65]
	v_pk_mul_f32 v[42:43], v[42:43], v[66:67]
	v_pk_fma_f32 v[40:41], v[210:211], s[96:97], v[40:41] op_sel_hi:[1,0,1]
	v_pk_fma_f32 v[42:43], v[212:213], s[96:97], v[42:43] op_sel_hi:[1,0,1]
	global_store_dwordx4 v151, v[40:43], s[18:19] offset:64
	v_pk_mul_f32 v[24:25], v[24:25], v[68:69]
	v_pk_mul_f32 v[26:27], v[26:27], v[70:71]
	v_pk_fma_f32 v[24:25], v[222:223], s[96:97], v[24:25] op_sel_hi:[1,0,1]
	v_pk_fma_f32 v[26:27], v[224:225], s[96:97], v[26:27] op_sel_hi:[1,0,1]
	global_store_dwordx4 v151, v[24:27], s[18:19] offset:128
	v_pk_mul_f32 v[8:9], v[8:9], v[72:73]
	v_pk_mul_f32 v[10:11], v[10:11], v[74:75]
	v_pk_fma_f32 v[8:9], v[226:227], s[96:97], v[8:9] op_sel_hi:[1,0,1]
	v_pk_fma_f32 v[10:11], v[228:229], s[96:97], v[10:11] op_sel_hi:[1,0,1]
	global_store_dwordx4 v151, v[8:11], s[18:19] offset:192
	v_pk_mul_f32 v[52:53], v[52:53], v[60:61]
	v_pk_mul_f32 v[54:55], v[54:55], v[62:63]
	v_pk_fma_f32 v[52:53], v[230:231], s[96:97], v[52:53] op_sel_hi:[1,0,1]
	v_pk_fma_f32 v[54:55], v[232:233], s[96:97], v[54:55] op_sel_hi:[1,0,1]
	global_store_dwordx4 v152, v[52:55], s[18:19] offset:0
	v_pk_mul_f32 v[36:37], v[36:37], v[64:65]
	v_pk_mul_f32 v[38:39], v[38:39], v[66:67]
	v_pk_fma_f32 v[36:37], v[234:235], s[96:97], v[36:37] op_sel_hi:[1,0,1]
	v_pk_fma_f32 v[38:39], v[236:237], s[96:97], v[38:39] op_sel_hi:[1,0,1]
	global_store_dwordx4 v152, v[36:39], s[18:19] offset:64
	v_pk_mul_f32 v[20:21], v[20:21], v[68:69]
	v_pk_mul_f32 v[22:23], v[22:23], v[70:71]
	v_pk_fma_f32 v[20:21], v[238:239], s[96:97], v[20:21] op_sel_hi:[1,0,1]
	v_pk_fma_f32 v[22:23], v[240:241], s[96:97], v[22:23] op_sel_hi:[1,0,1]
	global_store_dwordx4 v152, v[20:23], s[18:19] offset:128
	v_pk_mul_f32 v[4:5], v[4:5], v[72:73]
	v_pk_mul_f32 v[6:7], v[6:7], v[74:75]
	v_pk_fma_f32 v[4:5], v[242:243], s[96:97], v[4:5] op_sel_hi:[1,0,1]
	v_pk_fma_f32 v[6:7], v[244:245], s[96:97], v[6:7] op_sel_hi:[1,0,1]
	global_store_dwordx4 v152, v[4:7], s[18:19] offset:192
	v_pk_mul_f32 v[48:49], v[48:49], v[60:61]
	v_pk_mul_f32 v[50:51], v[50:51], v[62:63]
	v_pk_fma_f32 v[48:49], v[246:247], s[96:97], v[48:49] op_sel_hi:[1,0,1]
	v_pk_fma_f32 v[50:51], v[248:249], s[96:97], v[50:51] op_sel_hi:[1,0,1]
	global_store_dwordx4 v153, v[48:51], s[18:19] offset:0
	v_pk_mul_f32 v[32:33], v[32:33], v[64:65]
	v_pk_mul_f32 v[34:35], v[34:35], v[66:67]
	v_pk_fma_f32 v[32:33], v[158:159], s[96:97], v[32:33] op_sel_hi:[1,0,1]
	v_pk_fma_f32 v[34:35], v[160:161], s[96:97], v[34:35] op_sel_hi:[1,0,1]
	global_store_dwordx4 v153, v[32:35], s[18:19] offset:64
	v_pk_mul_f32 v[16:17], v[16:17], v[68:69]
	v_pk_mul_f32 v[18:19], v[18:19], v[70:71]
	v_pk_fma_f32 v[16:17], v[162:163], s[96:97], v[16:17] op_sel_hi:[1,0,1]
	v_pk_fma_f32 v[18:19], v[164:165], s[96:97], v[18:19] op_sel_hi:[1,0,1]
	global_store_dwordx4 v153, v[16:19], s[18:19] offset:128
	v_pk_mul_f32 v[0:1], v[0:1], v[72:73]
	v_pk_mul_f32 v[2:3], v[2:3], v[74:75]
	v_pk_fma_f32 v[0:1], v[154:155], s[96:97], v[0:1] op_sel_hi:[1,0,1]
	v_pk_fma_f32 v[2:3], v[156:157], s[96:97], v[2:3] op_sel_hi:[1,0,1]
	global_store_dwordx4 v153, v[0:3], s[18:19] offset:192
	s_add_i32 s6, s6, 1
	s_lshl_b32 s0, s6, 3
	v_readlane_b32 s4, v254, 36
	s_or_b32 s0, s0, s4
	v_readlane_b32 s4, v254, 37
	s_mul_i32 s0, s0, s4
	v_readlane_b32 s4, v254, 38
	s_add_i32 s0, s0, s4
	s_cmpk_gt_u32 s0, 0x5ff
	s_cbranch_scc1 .LBB0_1481
	s_branch .LBB0_1352
